# grid-barrier WAIT polls the cross-XCC arrival counter TOP >= (g+1)*nx instead of TOPGEN > g (one dependent atomic round trip less per barrier); on top of v23
# speedup vs baseline: 1.0037x; 1.0037x over previous
; __device__ __forceinline__ unsigned xb_ld(unsigned* p)              { return __hip_atomic_load(p, __ATOMIC_RELAXED, __HIP_MEMORY_SCOPE_AGENT); }
; #define XB_SPIN(cond, bar) do { unsigned _sp = 0; while (cond) { __builtin_amdgcn_s_sleep(1); \
;     if ((++_sp & 255u) == 0u) { if (xb_ld(&(bar)[XB_TMO])) break; if (_sp > XB_SPIN_CAP) { atomicAdd(&(bar)[XB_TMO], 1u); break; } } } } while (0)
; __device__ __forceinline__ bool xb_thread0(int wave) { return wave == 0 && hw_lane() == 0; }
; __device__ __forceinline__ void xcd_barrier_wait(const XcdBarrier& b) {
;     if (xb_thread0(b.wave)) {
;         const unsigned g = b.st[2];
;         XB_SPIN(xb_ld(&b.bar[XB_TOPGEN]) <= g, b.bar);
;         __builtin_amdgcn_fence(__ATOMIC_ACQUIRE, "agent");
;         asm volatile("s_waitcnt vmcnt(0)" ::: "memory");
;     }
;     __syncthreads();
; }
.LBB0_197:
	s_and_b64 vcc, exec, s[0:1]
	s_cbranch_vccnz .LBB0_214
	v_mbcnt_lo_u32_b32 v0, -1, 0
	v_mbcnt_hi_u32_b32 v0, -1, v0
	s_nop 0
	v_cmp_eq_u32_e32 vcc, 0, v0
	s_and_saveexec_b64 s[0:1], vcc
	s_cbranch_execz .LBB0_213
	s_add_i32 s2, 0, 0x24164
	v_mov_b32_e32 v0, s2
	v_mov_b32_e32 v2, 0x3000
	ds_read2_b32 v[0:1], v0 offset1:1
	global_load_dword v2, v2, s[66:67] offset:1024 sc1
	s_add_u32 s2, s66, 0x3400
	s_addc_u32 s3, s67, 0
	s_waitcnt lgkmcnt(0)
	v_mad_u32_u24 v0, v1, v0, v0
	v_add_u32_e32 v0, -1, v0
	s_waitcnt vmcnt(0)
	v_cmp_gt_u32_e32 vcc, v2, v0
	s_cbranch_vccnz .LBB0_212
	s_mov_b32 s10, 1
	v_mov_b32_e32 v1, 0
	s_branch .LBB0_202

; __device__ __forceinline__ unsigned xb_ld(unsigned* p)              { return __hip_atomic_load(p, __ATOMIC_RELAXED, __HIP_MEMORY_SCOPE_AGENT); }
; #define XB_SPIN(cond, bar) do { unsigned _sp = 0; while (cond) { __builtin_amdgcn_s_sleep(1); \
;     if ((++_sp & 255u) == 0u) { if (xb_ld(&(bar)[XB_TMO])) break; if (_sp > XB_SPIN_CAP) { atomicAdd(&(bar)[XB_TMO], 1u); break; } } } } while (0)
; __device__ __forceinline__ bool xb_thread0(int wave) { return wave == 0 && hw_lane() == 0; }
; __device__ __forceinline__ void xcd_barrier_wait(const XcdBarrier& b) {
;     if (xb_thread0(b.wave)) {
;         const unsigned g = b.st[2];
;         XB_SPIN(xb_ld(&b.bar[XB_TOPGEN]) <= g, b.bar);
;         __builtin_amdgcn_fence(__ATOMIC_ACQUIRE, "agent");
;         asm volatile("s_waitcnt vmcnt(0)" ::: "memory");
;     }
;     __syncthreads();
; }
.LBB0_629:
	s_and_b64 vcc, exec, s[0:1]
	s_cbranch_vccnz .LBB0_646
	v_mbcnt_lo_u32_b32 v0, -1, 0
	v_mbcnt_hi_u32_b32 v0, -1, v0
	s_nop 0
	v_cmp_eq_u32_e32 vcc, 0, v0
	s_and_saveexec_b64 s[2:3], vcc
	s_cbranch_execz .LBB0_645
	s_add_i32 s4, 0, 0x24164
	v_mov_b32_e32 v0, s4
	v_mov_b32_e32 v2, 0x3000
	ds_read2_b32 v[0:1], v0 offset1:1
	global_load_dword v2, v2, s[66:67] offset:1024 sc1
	s_add_u32 s4, s66, 0x3400
	s_addc_u32 s5, s67, 0
	s_waitcnt lgkmcnt(0)
	v_mad_u32_u24 v0, v1, v0, v0
	v_add_u32_e32 v0, -1, v0
	s_waitcnt vmcnt(0)
	v_cmp_gt_u32_e32 vcc, v2, v0
	s_cbranch_vccnz .LBB0_644
	s_mov_b32 s16, 1
	v_mov_b32_e32 v1, 0
	s_branch .LBB0_634

; #define LAS __attribute__((address_space(3)))
; __device__ __forceinline__ unsigned xb_ld(unsigned* p)              { return __hip_atomic_load(p, __ATOMIC_RELAXED, __HIP_MEMORY_SCOPE_AGENT); }
; #define XB_SPIN(cond, bar) do { unsigned _sp = 0; while (cond) { __builtin_amdgcn_s_sleep(1); \
;     if ((++_sp & 255u) == 0u) { if (xb_ld(&(bar)[XB_TMO])) break; if (_sp > XB_SPIN_CAP) { atomicAdd(&(bar)[XB_TMO], 1u); break; } } } } while (0)
; __device__ __forceinline__ bool xb_thread0(int wave) { return wave == 0 && hw_lane() == 0; }
;     __device__ __forceinline__ int tid_() const { return wave * 64 + lane_(); }
; __device__ __forceinline__ void xcd_barrier_wait(const XcdBarrier& b) {
;     if (xb_thread0(b.wave)) {
;         const unsigned g = b.st[2];
;         XB_SPIN(xb_ld(&b.bar[XB_TOPGEN]) <= g, b.bar);
; template <class Wait>
; __device__ __forceinline__ void out_unit(Frame& F, const Ptrs& P, int b, int c, int g, const Wait& wait) {
;     const bf16* XBC = (const bf16*)(P.ws + WS_XBC); const bf16* Z = (const bf16*)(P.ws + WS_Z); bf16* YG = (bf16*)(P.ws + WS_YG); float* SSQ = (float*)(P.ws + WS_SSQ);
;     const unsigned char* SB = (const unsigned char*)P.out;
;     const int wid = F.wave;
;     LAS unsigned char* lds = F.lds;
;     const int hl = wid >> 1, qh = wid & 1;
; #pragma unroll 1
;   for (int hh = 0; hh < 2; ++hh) {
;     int tid = F.tid_(); asm volatile("" : "+v"(tid));
;     const int lane = tid & 63, r32 = lane & 31, hi = lane >> 5;
;     const int h0 = 8 * g + 4 * hh, h = h0 + hl;
;     bf16x8 A0[2][8];
;     const int hl2 = tid >> 7, ch2 = tid & 7, rg2 = (tid >> 3) & 15, col2 = (h0 + hl2) * 64 + 8 * ch2;
;     if (hh == 0) {
;     float dv0, dv1; vec_load(F, P, b, c, h0, dv0, dv1);
;     ConvRaw R1; const int mat1 = tid >> 8, ch1 = tid & 15, rg1 = (tid >> 4) & 15, col1 = (mat1 ? 1024 : 1280) + g * 128 + 8 * ch1;
;     conv_load(R1, XBC, b, c, col1, rg1);
;     vec_compute(F, P, b, c, h0, dv0, dv1, nullptr);
;     conv_compute(R1, P.conv_w, P.conv_b, col1, rg1, PutRow{lds + (mat1 ? L_BROW : L_CIMG), ch1});
.LBB0_707:
	v_readlane_b32 s28, v252, 6
	v_readlane_b32 s29, v252, 7
	s_cmp_lt_i32 s28, 5
	s_cselect_b64 s[0:1], -1, 0
	s_cmp_gt_i32 s29, 4
	s_cselect_b64 s[2:3], -1, 0
	s_and_b64 s[0:1], s[0:1], s[2:3]
	s_andn2_b64 vcc, exec, s[0:1]
	v_readlane_b32 s30, v252, 8
	v_readlane_b32 s31, v252, 9
	s_cbranch_vccnz .LBB0_834
	v_readlane_b32 s0, v252, 4
	s_cmpk_gt_i32 s0, 0xff
	s_cbranch_scc1 .LBB0_769
	v_readlane_b32 s2, v252, 14
	v_readlane_b32 s3, v252, 15
	s_add_u32 s14, s2, 0x5c00000
	s_addc_u32 s15, s3, 0
	s_add_u32 s16, s2, 0x3c00000
	s_addc_u32 s17, s3, 0
	s_add_u32 s10, s2, 0x8c00000
	s_addc_u32 s11, s3, 0
	s_add_u32 s61, s2, 0xfe00000
	v_readlane_b32 s4, v252, 13
	s_addc_u32 s62, s3, 0
	s_lshr_b32 s63, s4, 7
	s_lshl_b32 s0, s63, 13
	s_add_i32 s69, 0, 0x10000
	v_readlane_b32 s1, v252, 5
	s_add_i32 s70, s69, s0
	s_lshl_b32 s0, s1, 11
	s_and_b32 s72, s0, 0xfffff000
	s_add_i32 s86, 0, 0x20000
	s_or_b32 s74, s0, 0x800
	s_lshl_b32 s76, s63, 14
	s_and_b32 s68, s4, 64
	s_lshl_b32 s71, s63, 2
	s_add_i32 s73, s86, s72
	s_add_i32 s75, s86, s74
	s_add_i32 s77, s69, s76
	s_cmpk_gt_u32 s4, 0xff
	s_cselect_b64 s[20:21], -1, 0
	s_lshl_b32 s1, s1, 6
	s_or_b32 s78, s71, 1
	s_or_b32 s79, s71, 2
	s_or_b32 s80, s71, 3
	s_or_b32 s81, s68, 31
	s_or_b32 s82, s68, 32
	s_or_b32 s83, s68, 63
	s_and_b32 s1, s1, 64
	s_add_u32 s1, s2, s1
	s_addc_u32 s2, s3, 0
	s_add_u32 s22, s1, 0xfc00000
	s_addc_u32 s23, s2, 0
	s_bitcmp1_b32 s4, 6
	s_cselect_b64 s[28:29], -1, 0
	s_cmp_eq_u32 s68, 0
	s_cselect_b32 s84, s37, s39
	s_cselect_b32 s85, s36, s38
	s_add_i32 s86, s86, s0
	s_add_u32 s30, s24, 0x1800
	s_addc_u32 s31, s25, 0
	s_add_u32 s36, s24, 0x3000
	s_addc_u32 s37, s25, 0
	s_add_u32 s38, s66, 0x3400
	s_mov_b32 s19, 0
	s_addc_u32 s39, s67, 0
	v_mov_b32_e32 v201, 0
	s_movk_i32 s87, 0xc00
	s_movk_i32 s88, 0x1000
	s_movk_i32 s89, 0x2000
	s_movk_i32 s90, 0x3000
	s_mov_b32 s91, 0x3fb8aa3b
	s_mov_b32 s92, 0xc2ce8ed0
	s_mov_b32 s93, 0x42b17218
	s_mov_b32 s94, 0x800000
	s_add_i32 s33, 0, 0x24164
	v_mov_b32_e32 v203, 0xc00
	v_mov_b32_e32 v212, 0x7f800000
	v_mov_b32_e32 v213, 0x3ffffffe
	v_mov_b32_e32 v214, 0x3ffffffc
	v_mov_b32_e32 v215, 0x3ffffff8
	v_mov_b32_e32 v216, 0x3ffffff0
	v_mov_b32_e32 v217, 0x3fffffe0
	v_mov_b32_e32 v218, 0x42000000
	v_mov_b32_e32 v219, 0x400
	v_mov_b32_e32 v220, 0x500
	v_mov_b32_e32 v221, 0x10000
	v_readlane_b32 s96, v252, 4
	s_branch .LBB0_711

; template <class Put>
; __device__ __forceinline__ void conv_compute(const ConvRaw& R, const float* cw, const float* cb, int col0, int rg, const Put& put) {
;     const f32x4 w0a = *(const f32x4*)(cw + col0), w0b = *(const f32x4*)(cw + col0 + 4), w1a = *(const f32x4*)(cw + XBCW + col0), w1b = *(const f32x4*)(cw + XBCW + col0 + 4);
;     const f32x4 w2a = *(const f32x4*)(cw + 2 * XBCW + col0), w2b = *(const f32x4*)(cw + 2 * XBCW + col0 + 4), ba = *(const f32x4*)(cb + col0), bb = *(const f32x4*)(cb + col0 + 4);
;     const int r0 = 8 * rg;
; #pragma unroll
;     for (int rr = 0; rr < 8; ++rr) {
;         const u32x4 xm = R.r[rr], x0 = R.r[rr + 1], xp = R.r[rr + 2]; u32x4 o;
; #pragma unroll
;         for (int e = 0; e < 4; ++e) {
;             const float wl0 = e < 2 ? w0a[2 * e] : w0b[2 * e - 4], wh0 = e < 2 ? w0a[2 * e + 1] : w0b[2 * e - 3];
;             const float wl1 = e < 2 ? w1a[2 * e] : w1b[2 * e - 4], wh1 = e < 2 ? w1a[2 * e + 1] : w1b[2 * e - 3];
;             const float wl2 = e < 2 ? w2a[2 * e] : w2b[2 * e - 4], wh2 = e < 2 ? w2a[2 * e + 1] : w2b[2 * e - 3];
;             const float bl = e < 2 ? ba[2 * e] : bb[2 * e - 4], bh = e < 2 ? ba[2 * e + 1] : bb[2 * e - 3];
;             const float vl = bl + wl0 * lo16(xm[e]) + wl1 * lo16(x0[e]) + wl2 * lo16(xp[e]);
;             const float vh = bh + wh0 * hi16(xm[e]) + wh1 * hi16(x0[e]) + wh2 * hi16(xp[e]);
;             o[e] = cvtpk(silu_fast(vl), silu_fast(vh));
;         }
;         put(r0 + rr, o);
;     }
; }
; __device__ __forceinline__ void vec_compute(Frame& F, const Ptrs& P, int b, int c, int h0, float v0, float v1, float* DEC) {
;     const int lane = F.lane_(), hl = F.wave >> 1, dir = F.wave & 1, h = h0 + hl;
;     const float A2 = -expf(dir ? P.alb[h] : P.alf[h]) * LOG2E;
;     float a0, a1, aend;
;     if (dir == 0) { const float p0 = incl_prefix(v0, lane), t0 = shfl_from(p0, 63), p1 = incl_prefix(v1, lane) + t0; a0 = A2 * p0; a1 = A2 * p1; aend = shfl_from(a1, 63); }
;     else { const float s1 = incl_suffix(v1, lane), t1 = shfl_from(s1, 0), s0 = incl_suffix(v0, lane) + t1; a0 = A2 * s0; a1 = A2 * s1; aend = shfl_from(a0, 0); }
;     LAS float* V = (LAS float*)(F.lds + L_VEC) + (hl * 2 + dir) * 512;
;     const float g0 = a0 - log2f(v0), g1 = a1 - log2f(v1);
;     V[lane] = a0; V[64 + lane] = a1; V[128 + lane] = g0; V[192 + lane] = g1; V[256 + lane] = v0; V[320 + lane] = v1;
.LBB0_724:
	v_or_b32_e32 v16, s97, v80
	v_cmp_ne_u32_e32 vcc, 0, v16
	v_lshlrev_b32_e32 v36, 2, v17
	v_lshlrev_b32_e32 v68, 16, v56
	v_cndmask_b32_e32 v81, 0, v11, vcc
	v_cndmask_b32_e32 v82, 0, v10, vcc
	v_cndmask_b32_e32 v72, 0, v9, vcc
	v_cndmask_b32_e32 v65, 0, v8, vcc
	v_cmp_eq_u32_e32 vcc, 15, v80
	s_and_b64 s[2:3], s[48:49], vcc
	v_cmp_gt_f32_e32 vcc, s94, v20
	v_cndmask_b32_e64 v76, v15, 0, s[2:3]
	v_cndmask_b32_e64 v77, v14, 0, s[2:3]
	v_cndmask_b32_e32 v8, 0, v218, vcc
	v_cndmask_b32_e64 v9, 0, 32, vcc
	v_cmp_gt_f32_e32 vcc, s94, v21
	v_ldexp_f32 v9, v20, v9
	v_log_f32_e32 v9, v9
	v_cndmask_b32_e64 v10, 0, 32, vcc
	v_ldexp_f32 v10, v21, v10
	v_log_f32_e32 v10, v10
	v_sub_f32_e32 v8, v9, v8
	v_cndmask_b32_e32 v9, 0, v218, vcc
	v_sub_f32_e32 v8, v19, v8
	v_sub_f32_e32 v9, v10, v9
	v_sub_f32_e32 v9, v18, v9
	v_lshl_add_u32 v10, v22, 2, s86
	ds_write2st64_b32 v10, v19, v18 offset1:1
	ds_write2st64_b32 v10, v8, v9 offset0:2 offset1:3
	ds_write2st64_b32 v10, v20, v21 offset0:4 offset1:5
	v_sub_f32_e32 v8, s4, v8
	v_sub_f32_e32 v9, s4, v9
	v_exp_f32_e32 v8, v8
	v_exp_f32_e32 v9, v9
	v_cndmask_b32_e64 v78, v13, 0, s[2:3]
	v_cndmask_b32_e64 v79, v12, 0, s[2:3]
	v_lshlrev_b32_e32 v64, 16, v65
	ds_write2st64_b32 v10, v8, v9 offset0:6 offset1:7
	v_cndmask_b32_e64 v8, v221, 0, s[0:1]
	v_add_u32_e32 v75, 0, v8
	global_load_dwordx4 v[8:11], v36, s[24:25] offset:16
	global_load_dwordx4 v[24:27], v36, s[24:25]
	global_load_dwordx4 v[16:19], v36, s[30:31] offset:16
	global_load_dwordx4 v[28:31], v36, s[30:31]
	global_load_dwordx4 v[12:15], v36, s[36:37] offset:16
	global_load_dwordx4 v[32:35], v36, s[36:37]
	global_load_dwordx4 v[20:23], v36, s[26:27] offset:16
	s_nop 0
	global_load_dwordx4 v[36:39], v36, s[26:27]
	v_and_b32_e32 v65, 0xffff0000, v65
	v_and_b32_e32 v69, 0xffff0000, v56
	v_lshlrev_b32_e32 v80, 11, v80
	v_or_b32_e32 v202, s68, v222
	v_or_b32_e32 v120, 32, v202
	v_lshlrev_b32_e32 v121, 8, v202
	v_lshlrev_b32_e32 v122, 8, v120
	v_cmp_eq_u32_e32 vcc, 15, v141
	v_lshlrev_b32_e32 v204, 3, v223
	s_waitcnt vmcnt(0)
	v_pk_fma_f32 v[64:65], v[24:25], v[64:65], v[36:37]
	s_nop 0
	v_pk_fma_f32 v[66:67], v[28:29], v[68:69], v[64:65]
	v_lshlrev_b32_e32 v64, 16, v60
	v_and_b32_e32 v65, 0xffff0000, v60
	v_pk_fma_f32 v[66:67], v[32:33], v[64:65], v[66:67]
	v_lshlrev_b32_e32 v60, 16, v61
	v_mul_f32_e32 v56, 0xbfb8aa3b, v66
	v_exp_f32_e32 v56, v56
	v_and_b32_e32 v61, 0xffff0000, v61
	v_add_f32_e32 v56, 1.0, v56
	v_rcp_f32_e32 v70, v56
	v_mul_f32_e32 v56, 0xbfb8aa3b, v67
	v_exp_f32_e32 v56, v56
	s_nop 0
	v_add_f32_e32 v56, 1.0, v56
	v_rcp_f32_e32 v71, v56
	s_nop 0
	v_pk_mul_f32 v[66:67], v[66:67], v[70:71]
	s_nop 0
	v_cvt_pk_bf16_f32 v56, v66, v67
	v_lshlrev_b32_e32 v66, 16, v72
	v_and_b32_e32 v67, 0xffff0000, v72
	v_pk_fma_f32 v[66:67], v[26:27], v[66:67], v[38:39]
	v_lshlrev_b32_e32 v70, 16, v57
	v_and_b32_e32 v71, 0xffff0000, v57
	v_pk_fma_f32 v[66:67], v[30:31], v[70:71], v[66:67]
	s_nop 0
	v_pk_fma_f32 v[66:67], v[34:35], v[60:61], v[66:67]
	s_nop 0
	v_mul_f32_e32 v57, 0xbfb8aa3b, v66
	v_exp_f32_e32 v57, v57
	s_nop 0
	v_add_f32_e32 v57, 1.0, v57
	v_rcp_f32_e32 v72, v57
	v_mul_f32_e32 v57, 0xbfb8aa3b, v67
	v_exp_f32_e32 v57, v57
	s_nop 0
	v_add_f32_e32 v57, 1.0, v57
	v_rcp_f32_e32 v73, v57
	s_nop 0
	v_pk_mul_f32 v[66:67], v[66:67], v[72:73]
	s_nop 0
	v_cvt_pk_bf16_f32 v57, v66, v67
	v_lshlrev_b32_e32 v66, 16, v82
	v_and_b32_e32 v67, 0xffff0000, v82
	v_pk_fma_f32 v[66:67], v[8:9], v[66:67], v[20:21]
	v_lshlrev_b32_e32 v72, 16, v58
	v_and_b32_e32 v73, 0xffff0000, v58
	v_pk_fma_f32 v[82:83], v[16:17], v[72:73], v[66:67]
	v_lshlrev_b32_e32 v66, 16, v62
	v_and_b32_e32 v67, 0xffff0000, v62
	v_pk_fma_f32 v[82:83], v[12:13], v[66:67], v[82:83]
	v_lshlrev_b32_e32 v62, 16, v63
	v_mul_f32_e32 v58, 0xbfb8aa3b, v82
	v_exp_f32_e32 v58, v58
	v_and_b32_e32 v63, 0xffff0000, v63
	v_add_f32_e32 v58, 1.0, v58
	v_rcp_f32_e32 v84, v58
	v_mul_f32_e32 v58, 0xbfb8aa3b, v83
	v_exp_f32_e32 v58, v58
	s_nop 0
	v_add_f32_e32 v58, 1.0, v58
	v_rcp_f32_e32 v85, v58
	s_nop 0
	v_pk_mul_f32 v[82:83], v[82:83], v[84:85]
	s_nop 0
	v_cvt_pk_bf16_f32 v58, v82, v83
	v_lshlrev_b32_e32 v82, 16, v81
	v_and_b32_e32 v83, 0xffff0000, v81
	v_pk_fma_f32 v[82:83], v[10:11], v[82:83], v[22:23]
	v_lshlrev_b32_e32 v84, 16, v59
	v_and_b32_e32 v85, 0xffff0000, v59
	v_pk_fma_f32 v[82:83], v[18:19], v[84:85], v[82:83]
	v_bitop3_b32 v81, v74, v132, 8 bitop3:0x6c
	v_pk_fma_f32 v[82:83], v[14:15], v[62:63], v[82:83]
	v_lshlrev_b32_e32 v81, 4, v81
	v_mul_f32_e32 v59, 0xbfb8aa3b, v82
	v_exp_f32_e32 v59, v59
	v_add3_u32 v80, v75, v80, v81
	v_add_f32_e32 v59, 1.0, v59
	v_rcp_f32_e32 v86, v59
	v_mul_f32_e32 v59, 0xbfb8aa3b, v83
	v_exp_f32_e32 v59, v59
	s_nop 0
	v_add_f32_e32 v59, 1.0, v59
	v_rcp_f32_e32 v87, v59
	s_nop 0
	v_pk_mul_f32 v[82:83], v[82:83], v[86:87]
	s_nop 0
	v_cvt_pk_bf16_f32 v59, v82, v83
	ds_write_b128 v80, v[56:59]
	v_pk_fma_f32 v[56:57], v[24:25], v[68:69], v[36:37]
	v_lshlrev_b32_e32 v58, 16, v52
	v_pk_fma_f32 v[56:57], v[28:29], v[64:65], v[56:57]
	v_and_b32_e32 v59, 0xffff0000, v52
	v_pk_fma_f32 v[56:57], v[32:33], v[58:59], v[56:57]
	v_add_u32_e32 v86, 0, v121
	v_mul_f32_e32 v52, 0xbfb8aa3b, v56
	v_exp_f32_e32 v52, v52
	v_add_u32_e32 v87, 0, v122
	v_add_f32_e32 v52, 1.0, v52
	v_rcp_f32_e32 v68, v52
	v_mul_f32_e32 v52, 0xbfb8aa3b, v57
	v_exp_f32_e32 v52, v52
	s_nop 0
	v_add_f32_e32 v52, 1.0, v52
	v_rcp_f32_e32 v69, v52
	s_nop 0
	v_pk_mul_f32 v[56:57], v[56:57], v[68:69]
	s_nop 0
	v_cvt_pk_bf16_f32 v80, v56, v57
	v_pk_fma_f32 v[56:57], v[26:27], v[70:71], v[38:39]
	v_lshlrev_b32_e32 v70, 16, v54
	v_pk_fma_f32 v[68:69], v[30:31], v[60:61], v[56:57]
	v_lshlrev_b32_e32 v56, 16, v53
; __device__ __forceinline__ unsigned cvtpk(float lo, float hi) { f32x2_t v = {lo, hi}; bf16x2_t b = __builtin_convertvector(v, bf16x2_t); return __builtin_bit_cast(unsigned, b); }
; __device__ __forceinline__ float lo16(unsigned u) { return __uint_as_float(u << 16); }
; __device__ __forceinline__ float hi16(unsigned u) { return __uint_as_float(u & 0xffff0000u); }
; __device__ __forceinline__ float silu_fast(float v) { return v * __builtin_amdgcn_rcpf(1.f + __builtin_amdgcn_exp2f(-v * LOG2E)); }
; __device__ __forceinline__ unsigned cvtpk(float lo, float hi) { f32x2_t v = {lo, hi}; bf16x2_t b = __builtin_convertvector(v, bf16x2_t); return __builtin_bit_cast(unsigned, b); }
; __device__ __forceinline__ float lo16(unsigned u) { return __uint_as_float(u << 16); }
; __device__ __forceinline__ float hi16(unsigned u) { return __uint_as_float(u & 0xffff0000u); }
; template <class Put>
; __device__ __forceinline__ void conv_compute(const ConvRaw& R, const float* cw, const float* cb, int col0, int rg, const Put& put) {
;     const f32x4 w0a = *(const f32x4*)(cw + col0), w0b = *(const f32x4*)(cw + col0 + 4), w1a = *(const f32x4*)(cw + XBCW + col0), w1b = *(const f32x4*)(cw + XBCW + col0 + 4);
;     const f32x4 w2a = *(const f32x4*)(cw + 2 * XBCW + col0), w2b = *(const f32x4*)(cw + 2 * XBCW + col0 + 4), ba = *(const f32x4*)(cb + col0), bb = *(const f32x4*)(cb + col0 + 4);
;     const int r0 = 8 * rg;
; #pragma unroll
;     for (int rr = 0; rr < 8; ++rr) {
;         const u32x4 xm = R.r[rr], x0 = R.r[rr + 1], xp = R.r[rr + 2]; u32x4 o;
; #pragma unroll
;         for (int e = 0; e < 4; ++e) {
;             const float wl0 = e < 2 ? w0a[2 * e] : w0b[2 * e - 4], wh0 = e < 2 ? w0a[2 * e + 1] : w0b[2 * e - 3];
;             const float wl1 = e < 2 ? w1a[2 * e] : w1b[2 * e - 4], wh1 = e < 2 ? w1a[2 * e + 1] : w1b[2 * e - 3];
;             const float wl2 = e < 2 ? w2a[2 * e] : w2b[2 * e - 4], wh2 = e < 2 ? w2a[2 * e + 1] : w2b[2 * e - 3];
;             const float bl = e < 2 ? ba[2 * e] : bb[2 * e - 4], bh = e < 2 ? ba[2 * e + 1] : bb[2 * e - 3];
;             const float vl = bl + wl0 * lo16(xm[e]) + wl1 * lo16(x0[e]) + wl2 * lo16(xp[e]);
;             const float vh = bh + wh0 * hi16(xm[e]) + wh1 * hi16(x0[e]) + wh2 * hi16(xp[e]);
;             o[e] = cvtpk(silu_fast(vl), silu_fast(vh));
;         }
;         put(r0 + rr, o);
;     }
; }
	v_and_b32_e32 v57, 0xffff0000, v53
	v_pk_fma_f32 v[52:53], v[34:35], v[56:57], v[68:69]
	v_and_b32_e32 v71, 0xffff0000, v54
	v_mul_f32_e32 v68, 0xbfb8aa3b, v52
	v_mul_f32_e32 v69, 0xbfb8aa3b, v53
	v_exp_f32_e32 v68, v68
	v_exp_f32_e32 v69, v69
	v_add_f32_e32 v68, 1.0, v68
	v_add_f32_e32 v69, 1.0, v69
	v_rcp_f32_e32 v68, v68
	v_rcp_f32_e32 v69, v69
	s_nop 0
	v_pk_mul_f32 v[52:53], v[52:53], v[68:69]
	s_nop 0
	v_cvt_pk_bf16_f32 v81, v52, v53
	v_pk_fma_f32 v[52:53], v[8:9], v[72:73], v[20:21]
	v_lshl_add_u32 v73, v222, 8, s70
	v_pk_fma_f32 v[52:53], v[16:17], v[66:67], v[52:53]
	v_or_b32_e32 v72, s97, v141
	v_pk_fma_f32 v[52:53], v[12:13], v[70:71], v[52:53]
	s_nop 0
	v_mul_f32_e32 v54, 0xbfb8aa3b, v52
	v_exp_f32_e32 v54, v54
	s_nop 0
	v_add_f32_e32 v54, 1.0, v54
	v_rcp_f32_e32 v68, v54
	v_mul_f32_e32 v54, 0xbfb8aa3b, v53
	v_exp_f32_e32 v54, v54
	s_nop 0
	v_add_f32_e32 v54, 1.0, v54
	v_rcp_f32_e32 v69, v54
	s_nop 0
	v_pk_mul_f32 v[52:53], v[52:53], v[68:69]
	s_nop 0
	v_cvt_pk_bf16_f32 v82, v52, v53
	v_pk_fma_f32 v[52:53], v[10:11], v[84:85], v[22:23]
	s_nop 0
	v_pk_fma_f32 v[68:69], v[18:19], v[62:63], v[52:53]
	v_lshlrev_b32_e32 v52, 16, v55
	v_and_b32_e32 v53, 0xffff0000, v55
	v_pk_fma_f32 v[54:55], v[14:15], v[52:53], v[68:69]
	s_nop 0
	v_mul_f32_e32 v68, 0xbfb8aa3b, v54
	v_mul_f32_e32 v69, 0xbfb8aa3b, v55
	v_exp_f32_e32 v68, v68
	v_exp_f32_e32 v69, v69
	v_add_f32_e32 v68, 1.0, v68
	v_add_f32_e32 v69, 1.0, v69
	v_rcp_f32_e32 v68, v68
	v_rcp_f32_e32 v69, v69
	s_nop 0
	v_pk_mul_f32 v[54:55], v[54:55], v[68:69]
	s_nop 0
	v_cvt_pk_bf16_f32 v83, v54, v55
	v_or_b32_e32 v54, 1, v74
	v_lshlrev_b32_e32 v55, 8, v54
	v_bitop3_b32 v54, v54, v132, 9 bitop3:0x6c
	v_lshlrev_b32_e32 v54, 4, v54
	v_add3_u32 v54, v75, v55, v54
	ds_write_b128 v54, v[80:83]
	v_pk_fma_f32 v[54:55], v[24:25], v[64:65], v[36:37]
	v_lshlrev_b32_e32 v68, 16, v48
	v_pk_fma_f32 v[54:55], v[28:29], v[58:59], v[54:55]
	v_and_b32_e32 v69, 0xffff0000, v48
	v_pk_fma_f32 v[54:55], v[32:33], v[68:69], v[54:55]
	s_nop 0
	v_mul_f32_e32 v48, 0xbfb8aa3b, v54
	v_exp_f32_e32 v48, v48
	s_nop 0
	v_add_f32_e32 v48, 1.0, v48
	v_rcp_f32_e32 v64, v48
	v_mul_f32_e32 v48, 0xbfb8aa3b, v55
	v_exp_f32_e32 v48, v48
	s_nop 0
	v_add_f32_e32 v48, 1.0, v48
	v_rcp_f32_e32 v65, v48
	v_lshlrev_b32_e32 v48, 16, v49
	v_and_b32_e32 v49, 0xffff0000, v49
	v_pk_mul_f32 v[54:55], v[54:55], v[64:65]
	s_nop 0
	v_cvt_pk_bf16_f32 v80, v54, v55
	v_pk_fma_f32 v[54:55], v[26:27], v[60:61], v[38:39]
	v_lshlrev_b32_e32 v64, 16, v50
	v_pk_fma_f32 v[54:55], v[30:31], v[56:57], v[54:55]
	v_and_b32_e32 v65, 0xffff0000, v50
	v_pk_fma_f32 v[54:55], v[34:35], v[48:49], v[54:55]
	s_nop 0
	v_mul_f32_e32 v60, 0xbfb8aa3b, v54
	v_mul_f32_e32 v61, 0xbfb8aa3b, v55
	v_exp_f32_e32 v60, v60
	v_exp_f32_e32 v61, v61
	v_add_f32_e32 v60, 1.0, v60
	v_add_f32_e32 v61, 1.0, v61
	v_rcp_f32_e32 v60, v60
	v_rcp_f32_e32 v61, v61
	s_nop 0
	v_pk_mul_f32 v[54:55], v[54:55], v[60:61]
	s_nop 0
	v_cvt_pk_bf16_f32 v81, v54, v55
	v_pk_fma_f32 v[54:55], v[8:9], v[66:67], v[20:21]
	s_nop 0
	v_pk_fma_f32 v[54:55], v[16:17], v[70:71], v[54:55]
	s_nop 0
	v_pk_fma_f32 v[54:55], v[12:13], v[64:65], v[54:55]
	s_nop 0
	v_mul_f32_e32 v50, 0xbfb8aa3b, v54
	v_exp_f32_e32 v50, v50
	s_nop 0
	v_add_f32_e32 v50, 1.0, v50
	v_rcp_f32_e32 v60, v50
	v_mul_f32_e32 v50, 0xbfb8aa3b, v55
	v_exp_f32_e32 v50, v50
	s_nop 0
	v_add_f32_e32 v50, 1.0, v50
	v_rcp_f32_e32 v61, v50
	s_nop 0
	v_pk_mul_f32 v[54:55], v[54:55], v[60:61]
	s_nop 0
	v_cvt_pk_bf16_f32 v82, v54, v55
	v_pk_fma_f32 v[54:55], v[10:11], v[62:63], v[22:23]
	v_lshlrev_b32_e32 v60, 16, v51
	v_pk_fma_f32 v[54:55], v[18:19], v[52:53], v[54:55]
	v_and_b32_e32 v61, 0xffff0000, v51
	v_pk_fma_f32 v[50:51], v[14:15], v[60:61], v[54:55]
	s_nop 0
	v_mul_f32_e32 v54, 0xbfb8aa3b, v50
	v_mul_f32_e32 v55, 0xbfb8aa3b, v51
	v_exp_f32_e32 v54, v54
	v_exp_f32_e32 v55, v55
	v_add_f32_e32 v54, 1.0, v54
	v_add_f32_e32 v55, 1.0, v55
	v_rcp_f32_e32 v54, v54
	v_rcp_f32_e32 v55, v55
	s_nop 0
	v_pk_mul_f32 v[50:51], v[50:51], v[54:55]
	s_nop 0
	v_cvt_pk_bf16_f32 v83, v50, v51
	v_or_b32_e32 v50, 2, v74
	v_lshlrev_b32_e32 v51, 8, v50
	v_bitop3_b32 v50, v50, v132, 10 bitop3:0x6c
	v_lshlrev_b32_e32 v50, 4, v50
	v_add3_u32 v50, v75, v51, v50
	ds_write_b128 v50, v[80:83]
	v_pk_fma_f32 v[50:51], v[24:25], v[58:59], v[36:37]
	v_lshlrev_b32_e32 v58, 16, v44
	v_pk_fma_f32 v[50:51], v[28:29], v[68:69], v[50:51]
	v_and_b32_e32 v59, 0xffff0000, v44
	v_pk_fma_f32 v[50:51], v[32:33], v[58:59], v[50:51]
	s_nop 0
	v_mul_f32_e32 v44, 0xbfb8aa3b, v50
	v_exp_f32_e32 v44, v44
	s_nop 0
	v_add_f32_e32 v44, 1.0, v44
	v_rcp_f32_e32 v54, v44
	v_mul_f32_e32 v44, 0xbfb8aa3b, v51
	v_exp_f32_e32 v44, v44
	s_nop 0
	v_add_f32_e32 v44, 1.0, v44
	v_rcp_f32_e32 v55, v44
	s_nop 0
	v_pk_mul_f32 v[50:51], v[50:51], v[54:55]
	s_nop 0
	v_cvt_pk_bf16_f32 v44, v50, v51
	v_pk_fma_f32 v[50:51], v[26:27], v[56:57], v[38:39]
	v_lshlrev_b32_e32 v56, 16, v45
	v_pk_fma_f32 v[50:51], v[30:31], v[48:49], v[50:51]
	v_and_b32_e32 v57, 0xffff0000, v45
	v_pk_fma_f32 v[50:51], v[34:35], v[56:57], v[50:51]
	s_nop 0
	v_mul_f32_e32 v45, 0xbfb8aa3b, v50
	v_exp_f32_e32 v45, v45
	s_nop 0
	v_add_f32_e32 v45, 1.0, v45
	v_rcp_f32_e32 v54, v45
	v_mul_f32_e32 v45, 0xbfb8aa3b, v51
	v_exp_f32_e32 v45, v45
	s_nop 0
	v_add_f32_e32 v45, 1.0, v45
	v_rcp_f32_e32 v55, v45
	s_nop 0
	v_pk_mul_f32 v[50:51], v[50:51], v[54:55]
	s_nop 0
	v_cvt_pk_bf16_f32 v45, v50, v51
	v_pk_fma_f32 v[50:51], v[8:9], v[70:71], v[20:21]
	v_lshlrev_b32_e32 v54, 16, v46
	v_pk_fma_f32 v[50:51], v[16:17], v[64:65], v[50:51]
	v_and_b32_e32 v55, 0xffff0000, v46
	v_pk_fma_f32 v[50:51], v[12:13], v[54:55], v[50:51]
	s_nop 0
	v_mul_f32_e32 v46, 0xbfb8aa3b, v50
; __device__ __forceinline__ unsigned cvtpk(float lo, float hi) { f32x2_t v = {lo, hi}; bf16x2_t b = __builtin_convertvector(v, bf16x2_t); return __builtin_bit_cast(unsigned, b); }
; __device__ __forceinline__ float lo16(unsigned u) { return __uint_as_float(u << 16); }
; __device__ __forceinline__ float hi16(unsigned u) { return __uint_as_float(u & 0xffff0000u); }
; __device__ __forceinline__ float silu_fast(float v) { return v * __builtin_amdgcn_rcpf(1.f + __builtin_amdgcn_exp2f(-v * LOG2E)); }
; __device__ __forceinline__ unsigned cvtpk(float lo, float hi) { f32x2_t v = {lo, hi}; bf16x2_t b = __builtin_convertvector(v, bf16x2_t); return __builtin_bit_cast(unsigned, b); }
; __device__ __forceinline__ float lo16(unsigned u) { return __uint_as_float(u << 16); }
; __device__ __forceinline__ float hi16(unsigned u) { return __uint_as_float(u & 0xffff0000u); }
; template <class Put>
; __device__ __forceinline__ void conv_compute(const ConvRaw& R, const float* cw, const float* cb, int col0, int rg, const Put& put) {
;     const f32x4 w0a = *(const f32x4*)(cw + col0), w0b = *(const f32x4*)(cw + col0 + 4), w1a = *(const f32x4*)(cw + XBCW + col0), w1b = *(const f32x4*)(cw + XBCW + col0 + 4);
;     const f32x4 w2a = *(const f32x4*)(cw + 2 * XBCW + col0), w2b = *(const f32x4*)(cw + 2 * XBCW + col0 + 4), ba = *(const f32x4*)(cb + col0), bb = *(const f32x4*)(cb + col0 + 4);
;     const int r0 = 8 * rg;
; #pragma unroll
;     for (int rr = 0; rr < 8; ++rr) {
;         const u32x4 xm = R.r[rr], x0 = R.r[rr + 1], xp = R.r[rr + 2]; u32x4 o;
; #pragma unroll
;         for (int e = 0; e < 4; ++e) {
;             const float wl0 = e < 2 ? w0a[2 * e] : w0b[2 * e - 4], wh0 = e < 2 ? w0a[2 * e + 1] : w0b[2 * e - 3];
;             const float wl1 = e < 2 ? w1a[2 * e] : w1b[2 * e - 4], wh1 = e < 2 ? w1a[2 * e + 1] : w1b[2 * e - 3];
;             const float wl2 = e < 2 ? w2a[2 * e] : w2b[2 * e - 4], wh2 = e < 2 ? w2a[2 * e + 1] : w2b[2 * e - 3];
;             const float bl = e < 2 ? ba[2 * e] : bb[2 * e - 4], bh = e < 2 ? ba[2 * e + 1] : bb[2 * e - 3];
;             const float vl = bl + wl0 * lo16(xm[e]) + wl1 * lo16(x0[e]) + wl2 * lo16(xp[e]);
;             const float vh = bh + wh0 * hi16(xm[e]) + wh1 * hi16(x0[e]) + wh2 * hi16(xp[e]);
;             o[e] = cvtpk(silu_fast(vl), silu_fast(vh));
;         }
;         put(r0 + rr, o);
;     }
; }
	v_exp_f32_e32 v46, v46
	s_nop 0
	v_add_f32_e32 v46, 1.0, v46
	v_rcp_f32_e32 v62, v46
	v_mul_f32_e32 v46, 0xbfb8aa3b, v51
	v_exp_f32_e32 v46, v46
	s_nop 0
	v_add_f32_e32 v46, 1.0, v46
	v_rcp_f32_e32 v63, v46
	s_nop 0
	v_pk_mul_f32 v[50:51], v[50:51], v[62:63]
	s_nop 0
	v_cvt_pk_bf16_f32 v46, v50, v51
	v_pk_fma_f32 v[50:51], v[10:11], v[52:53], v[22:23]
	v_lshlrev_b32_e32 v52, 16, v47
	v_pk_fma_f32 v[50:51], v[18:19], v[60:61], v[50:51]
	v_and_b32_e32 v53, 0xffff0000, v47
	v_pk_fma_f32 v[50:51], v[14:15], v[52:53], v[50:51]
	s_nop 0
	v_mul_f32_e32 v47, 0xbfb8aa3b, v50
	v_exp_f32_e32 v47, v47
	s_nop 0
	v_add_f32_e32 v47, 1.0, v47
	v_rcp_f32_e32 v62, v47
	v_mul_f32_e32 v47, 0xbfb8aa3b, v51
	v_exp_f32_e32 v47, v47
	s_nop 0
	v_add_f32_e32 v47, 1.0, v47
	v_rcp_f32_e32 v63, v47
	s_nop 0
	v_pk_mul_f32 v[50:51], v[50:51], v[62:63]
	s_nop 0
	v_cvt_pk_bf16_f32 v47, v50, v51
	v_or_b32_e32 v50, 3, v74
	v_lshlrev_b32_e32 v51, 8, v50
	v_bitop3_b32 v50, v50, v132, 11 bitop3:0x6c
	v_lshlrev_b32_e32 v50, 4, v50
	v_add3_u32 v50, v75, v51, v50
	ds_write_b128 v50, v[44:47]
	v_pk_fma_f32 v[44:45], v[24:25], v[68:69], v[36:37]
	v_lshlrev_b32_e32 v50, 16, v40
	v_pk_fma_f32 v[44:45], v[28:29], v[58:59], v[44:45]
	v_and_b32_e32 v51, 0xffff0000, v40
	v_pk_fma_f32 v[44:45], v[32:33], v[50:51], v[44:45]
	s_nop 0
	v_mul_f32_e32 v40, 0xbfb8aa3b, v44
	v_exp_f32_e32 v40, v40
	s_nop 0
	v_add_f32_e32 v40, 1.0, v40
	v_rcp_f32_e32 v46, v40
	v_mul_f32_e32 v40, 0xbfb8aa3b, v45
	v_exp_f32_e32 v40, v40
	s_nop 0
	v_add_f32_e32 v40, 1.0, v40
	v_rcp_f32_e32 v47, v40
	s_nop 0
	v_pk_mul_f32 v[44:45], v[44:45], v[46:47]
	s_nop 0
	v_cvt_pk_bf16_f32 v40, v44, v45
	v_pk_fma_f32 v[44:45], v[26:27], v[48:49], v[38:39]
	v_lshlrev_b32_e32 v48, 16, v41
	v_pk_fma_f32 v[44:45], v[30:31], v[56:57], v[44:45]
	v_and_b32_e32 v49, 0xffff0000, v41
	v_pk_fma_f32 v[44:45], v[34:35], v[48:49], v[44:45]
	s_nop 0
	v_mul_f32_e32 v41, 0xbfb8aa3b, v44
	v_exp_f32_e32 v41, v41
	s_nop 0
	v_add_f32_e32 v41, 1.0, v41
	v_rcp_f32_e32 v46, v41
	v_mul_f32_e32 v41, 0xbfb8aa3b, v45
	v_exp_f32_e32 v41, v41
	s_nop 0
	v_add_f32_e32 v41, 1.0, v41
	v_rcp_f32_e32 v47, v41
	s_nop 0
	v_pk_mul_f32 v[44:45], v[44:45], v[46:47]
	s_nop 0
	v_cvt_pk_bf16_f32 v41, v44, v45
	v_pk_fma_f32 v[44:45], v[8:9], v[64:65], v[20:21]
	v_lshlrev_b32_e32 v46, 16, v42
	v_pk_fma_f32 v[44:45], v[16:17], v[54:55], v[44:45]
	v_and_b32_e32 v47, 0xffff0000, v42
	v_pk_fma_f32 v[44:45], v[12:13], v[46:47], v[44:45]
	s_nop 0
	v_mul_f32_e32 v42, 0xbfb8aa3b, v44
	v_exp_f32_e32 v42, v42
	s_nop 0
	v_add_f32_e32 v42, 1.0, v42
	v_rcp_f32_e32 v62, v42
	v_mul_f32_e32 v42, 0xbfb8aa3b, v45
	v_exp_f32_e32 v42, v42
	s_nop 0
	v_add_f32_e32 v42, 1.0, v42
	v_rcp_f32_e32 v63, v42
	s_nop 0
	v_pk_mul_f32 v[44:45], v[44:45], v[62:63]
	s_nop 0
	v_cvt_pk_bf16_f32 v42, v44, v45
	v_pk_fma_f32 v[44:45], v[10:11], v[60:61], v[22:23]
	s_nop 0
	v_pk_fma_f32 v[60:61], v[18:19], v[52:53], v[44:45]
	v_lshlrev_b32_e32 v44, 16, v43
	v_and_b32_e32 v45, 0xffff0000, v43
	v_pk_fma_f32 v[60:61], v[14:15], v[44:45], v[60:61]
	v_pk_fma_f32 v[52:53], v[10:11], v[52:53], v[22:23]
	v_mul_f32_e32 v43, 0xbfb8aa3b, v60
	v_exp_f32_e32 v43, v43
	v_pk_fma_f32 v[52:53], v[18:19], v[44:45], v[52:53]
	v_pk_fma_f32 v[44:45], v[10:11], v[44:45], v[22:23]
	v_add_f32_e32 v43, 1.0, v43
	v_rcp_f32_e32 v62, v43
	v_mul_f32_e32 v43, 0xbfb8aa3b, v61
	v_exp_f32_e32 v43, v43
	s_nop 0
	v_add_f32_e32 v43, 1.0, v43
	v_rcp_f32_e32 v63, v43
	s_nop 0
	v_pk_mul_f32 v[60:61], v[60:61], v[62:63]
	s_nop 0
	v_cvt_pk_bf16_f32 v43, v60, v61
	v_or_b32_e32 v60, 4, v74
	v_lshlrev_b32_e32 v61, 8, v60
	v_bitop3_b32 v60, v60, v132, 12 bitop3:0x6c
	v_lshlrev_b32_e32 v60, 4, v60
	v_add3_u32 v60, v75, v61, v60
	ds_write_b128 v60, v[40:43]
	v_pk_fma_f32 v[40:41], v[24:25], v[58:59], v[36:37]
	v_lshlrev_b32_e32 v42, 16, v4
	v_pk_fma_f32 v[40:41], v[28:29], v[50:51], v[40:41]
	v_and_b32_e32 v43, 0xffff0000, v4
	v_pk_fma_f32 v[40:41], v[32:33], v[42:43], v[40:41]
	v_pk_fma_f32 v[50:51], v[24:25], v[50:51], v[36:37]
	v_mul_f32_e32 v4, 0xbfb8aa3b, v40
	v_exp_f32_e32 v4, v4
	v_pk_fma_f32 v[50:51], v[28:29], v[42:43], v[50:51]
	v_add_f32_e32 v4, 1.0, v4
	v_rcp_f32_e32 v58, v4
	v_mul_f32_e32 v4, 0xbfb8aa3b, v41
	v_exp_f32_e32 v4, v4
	s_nop 0
	v_add_f32_e32 v4, 1.0, v4
	v_rcp_f32_e32 v59, v4
	s_nop 0
	v_pk_mul_f32 v[40:41], v[40:41], v[58:59]
	s_nop 0
	v_cvt_pk_bf16_f32 v58, v40, v41
	v_pk_fma_f32 v[40:41], v[26:27], v[56:57], v[38:39]
	s_nop 0
	v_pk_fma_f32 v[56:57], v[30:31], v[48:49], v[40:41]
	v_lshlrev_b32_e32 v40, 16, v5
	v_and_b32_e32 v41, 0xffff0000, v5
	v_pk_fma_f32 v[4:5], v[34:35], v[40:41], v[56:57]
	v_pk_fma_f32 v[48:49], v[26:27], v[48:49], v[38:39]
	v_mul_f32_e32 v56, 0xbfb8aa3b, v4
	v_mul_f32_e32 v57, 0xbfb8aa3b, v5
	v_exp_f32_e32 v56, v56
	v_exp_f32_e32 v57, v57
	v_pk_fma_f32 v[48:49], v[30:31], v[40:41], v[48:49]
	v_add_f32_e32 v56, 1.0, v56
	v_add_f32_e32 v57, 1.0, v57
	v_rcp_f32_e32 v56, v56
	v_rcp_f32_e32 v57, v57
	s_nop 0
	v_pk_mul_f32 v[4:5], v[4:5], v[56:57]
	s_nop 0
	v_cvt_pk_bf16_f32 v59, v4, v5
	v_pk_fma_f32 v[4:5], v[8:9], v[54:55], v[20:21]
	s_nop 0
	v_pk_fma_f32 v[54:55], v[16:17], v[46:47], v[4:5]
	v_lshlrev_b32_e32 v4, 16, v6
	v_and_b32_e32 v5, 0xffff0000, v6
	v_pk_fma_f32 v[54:55], v[12:13], v[4:5], v[54:55]
	v_pk_fma_f32 v[46:47], v[8:9], v[46:47], v[20:21]
	v_mul_f32_e32 v6, 0xbfb8aa3b, v54
	v_exp_f32_e32 v6, v6
	v_pk_fma_f32 v[46:47], v[16:17], v[4:5], v[46:47]
	v_pk_fma_f32 v[4:5], v[8:9], v[4:5], v[20:21]
	v_add_f32_e32 v6, 1.0, v6
	v_rcp_f32_e32 v56, v6
	v_mul_f32_e32 v6, 0xbfb8aa3b, v55
	v_exp_f32_e32 v6, v6
	s_nop 0
	v_add_f32_e32 v6, 1.0, v6
	v_rcp_f32_e32 v57, v6
	v_lshlrev_b32_e32 v6, 16, v7
; __device__ __forceinline__ unsigned cvtpk(float lo, float hi) { f32x2_t v = {lo, hi}; bf16x2_t b = __builtin_convertvector(v, bf16x2_t); return __builtin_bit_cast(unsigned, b); }
; __device__ __forceinline__ float lo16(unsigned u) { return __uint_as_float(u << 16); }
; __device__ __forceinline__ float hi16(unsigned u) { return __uint_as_float(u & 0xffff0000u); }
; __device__ __forceinline__ void conv_load(ConvRaw& R, const bf16* XBC, int b, int c, int col0, int rg) {
;     const int r0 = 8 * rg;
; #pragma unroll
;     for (int i = 0; i < 10; ++i) { int t = c * 128 + r0 - 1 + i; t = t < 0 ? 0 : (t > SEQ - 1 ? SEQ - 1 : t); R.r[i] = *(const u32x4*)(XBC + ((size_t)b * SEQ + t) * XBCW + col0); }
;     if (c == 0 && rg == 0) R.r[0] = (u32x4){0u, 0u, 0u, 0u};
;     if (c == 63 && rg == 15) R.r[9] = (u32x4){0u, 0u, 0u, 0u};
; }
; template <class Put>
; __device__ __forceinline__ void conv_compute(const ConvRaw& R, const float* cw, const float* cb, int col0, int rg, const Put& put) {
;     const f32x4 w0a = *(const f32x4*)(cw + col0), w0b = *(const f32x4*)(cw + col0 + 4), w1a = *(const f32x4*)(cw + XBCW + col0), w1b = *(const f32x4*)(cw + XBCW + col0 + 4);
;     const f32x4 w2a = *(const f32x4*)(cw + 2 * XBCW + col0), w2b = *(const f32x4*)(cw + 2 * XBCW + col0 + 4), ba = *(const f32x4*)(cb + col0), bb = *(const f32x4*)(cb + col0 + 4);
;     const int r0 = 8 * rg;
; #pragma unroll
;     for (int rr = 0; rr < 8; ++rr) {
;         const u32x4 xm = R.r[rr], x0 = R.r[rr + 1], xp = R.r[rr + 2]; u32x4 o;
; #pragma unroll
;         for (int e = 0; e < 4; ++e) {
;             const float wl0 = e < 2 ? w0a[2 * e] : w0b[2 * e - 4], wh0 = e < 2 ? w0a[2 * e + 1] : w0b[2 * e - 3];
;             const float wl1 = e < 2 ? w1a[2 * e] : w1b[2 * e - 4], wh1 = e < 2 ? w1a[2 * e + 1] : w1b[2 * e - 3];
;             const float wl2 = e < 2 ? w2a[2 * e] : w2b[2 * e - 4], wh2 = e < 2 ? w2a[2 * e + 1] : w2b[2 * e - 3];
;             const float bl = e < 2 ? ba[2 * e] : bb[2 * e - 4], bh = e < 2 ? ba[2 * e + 1] : bb[2 * e - 3];
;             const float vl = bl + wl0 * lo16(xm[e]) + wl1 * lo16(x0[e]) + wl2 * lo16(xp[e]);
;             const float vh = bh + wh0 * hi16(xm[e]) + wh1 * hi16(x0[e]) + wh2 * hi16(xp[e]);
;             o[e] = cvtpk(silu_fast(vl), silu_fast(vh));
;         }
;         put(r0 + rr, o);
;     }
; }
	v_and_b32_e32 v7, 0xffff0000, v7
	v_pk_fma_f32 v[52:53], v[14:15], v[6:7], v[52:53]
	v_pk_mul_f32 v[54:55], v[54:55], v[56:57]
	v_pk_fma_f32 v[44:45], v[18:19], v[6:7], v[44:45]
	v_cvt_pk_bf16_f32 v60, v54, v55
	v_mul_f32_e32 v54, 0xbfb8aa3b, v52
	v_mul_f32_e32 v55, 0xbfb8aa3b, v53
	v_exp_f32_e32 v54, v54
	v_exp_f32_e32 v55, v55
	v_add_f32_e32 v54, 1.0, v54
	v_add_f32_e32 v55, 1.0, v55
	v_rcp_f32_e32 v54, v54
	v_rcp_f32_e32 v55, v55
	s_nop 0
	v_pk_mul_f32 v[52:53], v[52:53], v[54:55]
	s_nop 0
	v_cvt_pk_bf16_f32 v61, v52, v53
	v_or_b32_e32 v52, 5, v74
	v_lshlrev_b32_e32 v53, 8, v52
	v_bitop3_b32 v52, v52, v132, 13 bitop3:0x6c
	v_lshlrev_b32_e32 v52, 4, v52
	v_add3_u32 v52, v75, v53, v52
	ds_write_b128 v52, v[58:61]
	v_lshlrev_b32_e32 v52, 16, v0
	v_and_b32_e32 v53, 0xffff0000, v0
	v_pk_fma_f32 v[50:51], v[32:33], v[52:53], v[50:51]
	s_nop 0
	v_mul_f32_e32 v0, 0xbfb8aa3b, v50
	v_exp_f32_e32 v0, v0
	s_nop 0
	v_add_f32_e32 v0, 1.0, v0
	v_rcp_f32_e32 v54, v0
	v_mul_f32_e32 v0, 0xbfb8aa3b, v51
	v_exp_f32_e32 v0, v0
	s_nop 0
	v_add_f32_e32 v0, 1.0, v0
	v_rcp_f32_e32 v55, v0
	s_nop 0
	v_pk_mul_f32 v[50:51], v[50:51], v[54:55]
	s_nop 0
	v_cvt_pk_bf16_f32 v0, v50, v51
	v_lshlrev_b32_e32 v50, 16, v1
	v_and_b32_e32 v51, 0xffff0000, v1
	v_pk_fma_f32 v[48:49], v[34:35], v[50:51], v[48:49]
	s_nop 0
	v_mul_f32_e32 v1, 0xbfb8aa3b, v48
	v_exp_f32_e32 v1, v1
	s_nop 0
	v_add_f32_e32 v1, 1.0, v1
	v_rcp_f32_e32 v54, v1
	v_mul_f32_e32 v1, 0xbfb8aa3b, v49
	v_exp_f32_e32 v1, v1
	s_nop 0
	v_add_f32_e32 v1, 1.0, v1
	v_rcp_f32_e32 v55, v1
	s_nop 0
	v_pk_mul_f32 v[48:49], v[48:49], v[54:55]
	s_nop 0
	v_cvt_pk_bf16_f32 v1, v48, v49
	v_lshlrev_b32_e32 v48, 16, v2
	v_and_b32_e32 v49, 0xffff0000, v2
	v_pk_fma_f32 v[46:47], v[12:13], v[48:49], v[46:47]
	v_pk_fma_f32 v[4:5], v[16:17], v[48:49], v[4:5]
	v_mul_f32_e32 v2, 0xbfb8aa3b, v46
	v_exp_f32_e32 v2, v2
	s_nop 0
	v_add_f32_e32 v2, 1.0, v2
	v_rcp_f32_e32 v54, v2
	v_mul_f32_e32 v2, 0xbfb8aa3b, v47
	v_exp_f32_e32 v2, v2
	s_nop 0
	v_add_f32_e32 v2, 1.0, v2
	v_rcp_f32_e32 v55, v2
	s_nop 0
	v_pk_mul_f32 v[46:47], v[46:47], v[54:55]
	s_nop 0
	v_cvt_pk_bf16_f32 v2, v46, v47
	v_lshlrev_b32_e32 v46, 16, v3
	v_and_b32_e32 v47, 0xffff0000, v3
	v_pk_fma_f32 v[44:45], v[14:15], v[46:47], v[44:45]
	s_nop 0
	v_mul_f32_e32 v3, 0xbfb8aa3b, v44
	v_exp_f32_e32 v3, v3
	s_nop 0
	v_add_f32_e32 v3, 1.0, v3
	v_rcp_f32_e32 v54, v3
	v_mul_f32_e32 v3, 0xbfb8aa3b, v45
	v_exp_f32_e32 v3, v3
	s_nop 0
	v_add_f32_e32 v3, 1.0, v3
	v_rcp_f32_e32 v55, v3
	s_nop 0
	v_pk_mul_f32 v[44:45], v[44:45], v[54:55]
	s_nop 0
	v_cvt_pk_bf16_f32 v3, v44, v45
	v_or_b32_e32 v44, 6, v74
	v_lshlrev_b32_e32 v45, 8, v44
	v_bitop3_b32 v44, v44, v132, 14 bitop3:0x6c
	v_lshlrev_b32_e32 v44, 4, v44
	v_add3_u32 v44, v75, v45, v44
	ds_write_b128 v44, v[0:3]
	v_pk_fma_f32 v[2:3], v[24:25], v[42:43], v[36:37]
	v_lshlrev_b32_e32 v0, 16, v79
	v_and_b32_e32 v1, 0xffff0000, v79
	v_pk_fma_f32 v[2:3], v[28:29], v[52:53], v[2:3]
	v_pk_fma_f32 v[24:25], v[26:27], v[40:41], v[38:39]
	v_pk_fma_f32 v[0:1], v[32:33], v[0:1], v[2:3]
	v_pk_fma_f32 v[24:25], v[30:31], v[50:51], v[24:25]
	v_mul_f32_e32 v2, 0xbfb8aa3b, v0
	v_mul_f32_e32 v3, 0xbfb8aa3b, v1
	v_exp_f32_e32 v2, v2
	v_exp_f32_e32 v3, v3
	v_add_f32_e32 v2, 1.0, v2
	v_add_f32_e32 v3, 1.0, v3
	v_rcp_f32_e32 v2, v2
	v_rcp_f32_e32 v3, v3
	s_nop 0
	v_pk_mul_f32 v[0:1], v[0:1], v[2:3]
	v_lshlrev_b32_e32 v2, 16, v78
	v_and_b32_e32 v3, 0xffff0000, v78
	v_pk_fma_f32 v[2:3], v[34:35], v[2:3], v[24:25]
	v_cvt_pk_bf16_f32 v0, v0, v1
	v_mul_f32_e32 v1, 0xbfb8aa3b, v2
	v_exp_f32_e32 v1, v1
	s_nop 0
	v_add_f32_e32 v1, 1.0, v1
	v_rcp_f32_e32 v24, v1
	v_mul_f32_e32 v1, 0xbfb8aa3b, v3
	v_exp_f32_e32 v1, v1
	s_nop 0
	v_add_f32_e32 v1, 1.0, v1
	v_rcp_f32_e32 v25, v1
	s_nop 0
	v_pk_mul_f32 v[2:3], v[2:3], v[24:25]
	s_nop 0
	v_cvt_pk_bf16_f32 v1, v2, v3
	v_lshlrev_b32_e32 v2, 16, v77
	v_and_b32_e32 v3, 0xffff0000, v77
	v_pk_fma_f32 v[2:3], v[12:13], v[2:3], v[4:5]
	s_nop 0
	v_mul_f32_e32 v4, 0xbfb8aa3b, v2
	v_mul_f32_e32 v5, 0xbfb8aa3b, v3
	v_exp_f32_e32 v4, v4
	v_exp_f32_e32 v5, v5
	v_add_f32_e32 v4, 1.0, v4
	v_add_f32_e32 v5, 1.0, v5
	v_rcp_f32_e32 v4, v4
	v_rcp_f32_e32 v5, v5
	s_nop 0
	v_pk_mul_f32 v[2:3], v[2:3], v[4:5]
	v_pk_fma_f32 v[4:5], v[10:11], v[6:7], v[22:23]
	v_lshlrev_b32_e32 v6, 16, v76
	v_pk_fma_f32 v[4:5], v[18:19], v[46:47], v[4:5]
	v_and_b32_e32 v7, 0xffff0000, v76
	v_pk_fma_f32 v[4:5], v[14:15], v[6:7], v[4:5]
	v_cvt_pk_bf16_f32 v2, v2, v3
	v_mul_f32_e32 v3, 0xbfb8aa3b, v4
	v_exp_f32_e32 v3, v3
	s_nop 0
	v_add_f32_e32 v3, 1.0, v3
	v_rcp_f32_e32 v6, v3
	v_mul_f32_e32 v3, 0xbfb8aa3b, v5
	v_exp_f32_e32 v3, v3
	s_nop 0
	v_add_f32_e32 v3, 1.0, v3
	v_rcp_f32_e32 v7, v3
	s_nop 0
	v_pk_mul_f32 v[4:5], v[4:5], v[6:7]
	s_nop 0
	v_cvt_pk_bf16_f32 v3, v4, v5
	v_bitop3_b32 v5, v74, v224, 7 bitop3:0x36
	v_or_b32_e32 v4, 7, v74
	v_lshlrev_b32_e32 v5, 4, v5
	v_lshlrev_b32_e32 v4, 8, v4
	v_and_b32_e32 v5, 0xf0, v5
	v_add3_u32 v4, v75, v4, v5
	ds_write_b128 v4, v[0:3]
	v_max_i32_e32 v2, 0, v143
	v_mov_b32_e32 v3, v201
	v_lshl_add_u64 v[0:1], v[130:131], 1, s[14:15]
	v_lshl_add_u64 v[2:3], s[42:43], 0, v[2:3]
	v_mad_u64_u32 v[4:5], s[0:1], v2, s87, v[0:1]
	v_or_b32_e32 v2, s42, v144
	v_mad_i32_i24 v5, v3, s87, v5
	v_mad_u64_u32 v[2:3], s[0:1], v2, s87, v[0:1]
	v_mad_i32_i24 v3, s43, v203, v3
	s_waitcnt lgkmcnt(0)
	s_barrier
; #define LAS __attribute__((address_space(3)))
; __device__ __forceinline__ unsigned cvtpk(float lo, float hi) { f32x2_t v = {lo, hi}; bf16x2_t b = __builtin_convertvector(v, bf16x2_t); return __builtin_bit_cast(unsigned, b); }
; __device__ __forceinline__ unsigned cvtpk(float lo, float hi) { f32x2_t v = {lo, hi}; bf16x2_t b = __builtin_convertvector(v, bf16x2_t); return __builtin_bit_cast(unsigned, b); }
; template <class Wait>
; __device__ __forceinline__ void out_unit(Frame& F, const Ptrs& P, int b, int c, int g, const Wait& wait) {
;     ...
;     ConvRaw R2;
;     conv_load(R2, XBC, b, c, col2, rg2);
;     {
;         const int sblk = wid >> 1, s = 32 * sblk + r32;
;         f32x16 d0 = f32x16{}, d1 = f32x16{};
;         const int q0 = 64 * (wid & 1) + r32, q1 = q0 + 32;
; #pragma unroll
;         for (int ks = 0; ks < 8; ++ks) { const int chn = 2 * ks + hi;
;             const bf16x8 a = *(const LAS bf16x8*)(lds + L_BROW + s * 256 + ((chn ^ (s & 15)) * 16));
;             const bf16x8 c0 = *(const LAS bf16x8*)(lds + L_CIMG + q0 * 256 + ((chn ^ (q0 & 15)) * 16)), c1 = *(const LAS bf16x8*)(lds + L_CIMG + q1 * 256 + ((chn ^ (q1 & 15)) * 16));
;             d0 = __builtin_amdgcn_mfma_f32_32x32x16_bf16(a, c0, d0, 0, 0, 0); d1 = __builtin_amdgcn_mfma_f32_32x32x16_bf16(a, c1, d1, 0, 0, 0); }
; #pragma unroll
;         for (int g4 = 0; g4 < 4; ++g4) { const int chs = 4 * sblk + g4;
;             u32x2 w0; w0.x = cvtpk(d0[4 * g4], d0[4 * g4 + 1]); w0.y = cvtpk(d0[4 * g4 + 2], d0[4 * g4 + 3]);
;             u32x2 w1; w1.x = cvtpk(d1[4 * g4], d1[4 * g4 + 1]); w1.y = cvtpk(d1[4 * g4 + 2], d1[4 * g4 + 3]);
;             *(LAS u32x2*)(lds + L_CB + q0 * 256 + ((chs ^ (q0 & 15)) * 16) + hi * 8) = w0; *(LAS u32x2*)(lds + L_CB + q1 * 256 + ((chs ^ (q1 & 15)) * 16) + hi * 8) = w1; }
;     }
;     __syncthreads();
	global_load_dwordx4 v[68:71], v[4:5], off
	global_load_dwordx4 v[60:63], v[2:3], off
	v_add_u32_e32 v2, 2, v143
	v_mov_b32_e32 v3, v201
	v_lshl_add_u64 v[2:3], s[42:43], 0, v[2:3]
	v_mad_u64_u32 v[4:5], s[0:1], v2, s87, v[0:1]
	v_mad_i32_i24 v5, v3, s87, v5
	v_add_u32_e32 v2, 3, v143
	v_mov_b32_e32 v3, v201
	v_lshl_add_u64 v[2:3], s[42:43], 0, v[2:3]
	global_load_dwordx4 v[56:59], v[4:5], off
	v_mad_u64_u32 v[4:5], s[0:1], v2, s87, v[0:1]
	v_mad_i32_i24 v5, v3, s87, v5
	v_add_u32_e32 v2, 4, v143
	v_mov_b32_e32 v3, v201
	v_lshl_add_u64 v[2:3], s[42:43], 0, v[2:3]
	global_load_dwordx4 v[52:55], v[4:5], off
	v_mad_u64_u32 v[4:5], s[0:1], v2, s87, v[0:1]
	v_mad_i32_i24 v5, v3, s87, v5
	v_add_u32_e32 v2, 5, v143
	v_mov_b32_e32 v3, v201
	v_lshl_add_u64 v[2:3], s[42:43], 0, v[2:3]
	global_load_dwordx4 v[48:51], v[4:5], off
	v_mad_u64_u32 v[4:5], s[0:1], v2, s87, v[0:1]
	v_mad_i32_i24 v5, v3, s87, v5
	v_add_u32_e32 v2, 6, v143
	v_mov_b32_e32 v3, v201
	v_lshl_add_u64 v[2:3], s[42:43], 0, v[2:3]
	global_load_dwordx4 v[44:47], v[4:5], off
	v_mad_u64_u32 v[4:5], s[0:1], v2, s87, v[0:1]
	v_mad_i32_i24 v5, v3, s87, v5
	v_add_u32_e32 v2, 7, v143
	v_mov_b32_e32 v3, v201
	v_lshl_add_u64 v[2:3], s[42:43], 0, v[2:3]
	global_load_dwordx4 v[40:43], v[4:5], off
	v_mad_u64_u32 v[4:5], s[0:1], v2, s87, v[0:1]
	v_mad_i32_i24 v5, v3, s87, v5
	v_add_u32_e32 v2, 8, v143
	v_mov_b32_e32 v3, v201
	v_lshl_add_u64 v[2:3], s[42:43], 0, v[2:3]
	global_load_dwordx4 v[36:39], v[4:5], off
	v_mad_u64_u32 v[4:5], s[0:1], v2, s87, v[0:1]
	v_add_u32_e32 v2, 9, v143
	v_min_u32_e32 v2, 0x1fff, v2
	v_or_b32_e32 v2, s42, v2
	v_mad_u64_u32 v[0:1], s[0:1], v2, s87, v[0:1]
	v_mad_i32_i24 v5, v3, s87, v5
	v_mad_i32_i24 v1, s43, v203, v1
	global_load_dwordx4 v[32:35], v[4:5], off
	global_load_dwordx4 v[64:67], v[0:1], off
	v_xor_b32_e32 v0, v223, v132
	v_lshlrev_b32_e32 v123, 4, v0
	v_add_u32_e32 v0, v73, v123
	ds_read_b128 v[0:3], v0
	v_add_u32_e32 v4, v86, v123
	v_add_u32_e32 v8, v87, v123
	ds_read_b128 v[4:7], v4
	ds_read_b128 v[8:11], v8
	v_bitop3_b32 v74, v223, v132, 2 bitop3:0x36
	v_lshlrev_b32_e32 v124, 4, v74
	v_add_u32_e32 v74, v73, v124
	ds_read_b128 v[74:77], v74
	s_waitcnt lgkmcnt(2)
	v_mfma_f32_32x32x16_bf16 v[16:31], v[0:3], v[4:7], 0
	v_add_u32_e32 v78, v86, v124
	v_add_u32_e32 v82, v87, v124
	ds_read_b128 v[78:81], v78
	ds_read_b128 v[82:85], v82
	s_and_b64 s[0:1], s[48:49], vcc
	v_cmp_ne_u32_e32 vcc, 0, v72
	s_waitcnt vmcnt(0)
	v_cndmask_b32_e64 v72, v67, 0, s[0:1]
	s_waitcnt lgkmcnt(3)
	v_mfma_f32_32x32x16_bf16 v[0:15], v[0:3], v[8:11], 0
	v_cndmask_b32_e32 v68, 0, v68, vcc
	v_and_b32_e32 v67, 0xffff0000, v60
	s_waitcnt lgkmcnt(1)
	v_mfma_f32_32x32x16_bf16 v[16:31], v[74:77], v[78:81], v[16:31]
	s_waitcnt lgkmcnt(0)
	v_mfma_f32_32x32x16_bf16 v[0:15], v[74:77], v[82:85], v[0:15]
	v_bitop3_b32 v74, v223, v132, 4 bitop3:0x36
	v_lshlrev_b32_e32 v125, 4, v74
	v_add_u32_e32 v74, v73, v125
	ds_read_b128 v[74:77], v74
	v_add_u32_e32 v78, v86, v125
	v_add_u32_e32 v82, v87, v125
	ds_read_b128 v[78:81], v78
	ds_read_b128 v[82:85], v82
	s_waitcnt lgkmcnt(1)
	v_mfma_f32_32x32x16_bf16 v[16:31], v[74:77], v[78:81], v[16:31]
	s_waitcnt lgkmcnt(0)
	v_mfma_f32_32x32x16_bf16 v[0:15], v[74:77], v[82:85], v[0:15]
	v_bitop3_b32 v74, v223, v132, 6 bitop3:0x36
	v_lshlrev_b32_e32 v126, 4, v74
	v_add_u32_e32 v74, v73, v126
	ds_read_b128 v[74:77], v74
	v_add_u32_e32 v78, v86, v126
	v_add_u32_e32 v82, v87, v126
	ds_read_b128 v[78:81], v78
	ds_read_b128 v[82:85], v82
	s_waitcnt lgkmcnt(1)
	v_mfma_f32_32x32x16_bf16 v[16:31], v[74:77], v[78:81], v[16:31]
	s_waitcnt lgkmcnt(0)
	v_mfma_f32_32x32x16_bf16 v[0:15], v[74:77], v[82:85], v[0:15]
	v_bitop3_b32 v74, v223, v132, 8 bitop3:0x36
	v_lshlrev_b32_e32 v127, 4, v74
	v_add_u32_e32 v74, v73, v127
	ds_read_b128 v[74:77], v74
	v_add_u32_e32 v78, v86, v127
	v_add_u32_e32 v82, v87, v127
	ds_read_b128 v[78:81], v78
	ds_read_b128 v[82:85], v82
	s_waitcnt lgkmcnt(1)
	v_mfma_f32_32x32x16_bf16 v[16:31], v[74:77], v[78:81], v[16:31]
	s_waitcnt lgkmcnt(0)
	v_mfma_f32_32x32x16_bf16 v[0:15], v[74:77], v[82:85], v[0:15]
	v_bitop3_b32 v74, v223, v132, 10 bitop3:0x36
	v_lshlrev_b32_e32 v133, 4, v74
	v_add_u32_e32 v74, v73, v133
	ds_read_b128 v[74:77], v74
	v_add_u32_e32 v78, v86, v133
	v_add_u32_e32 v82, v87, v133
	ds_read_b128 v[78:81], v78
	ds_read_b128 v[82:85], v82
	s_waitcnt lgkmcnt(1)
	v_mfma_f32_32x32x16_bf16 v[16:31], v[74:77], v[78:81], v[16:31]
	s_waitcnt lgkmcnt(0)
	v_mfma_f32_32x32x16_bf16 v[0:15], v[74:77], v[82:85], v[0:15]
	v_bitop3_b32 v74, v223, v132, 12 bitop3:0x36
	v_lshlrev_b32_e32 v134, 4, v74
	v_add_u32_e32 v74, v73, v134
	ds_read_b128 v[74:77], v74
	v_add_u32_e32 v78, v86, v134
	v_add_u32_e32 v82, v87, v134
	ds_read_b128 v[78:81], v78
	ds_read_b128 v[82:85], v82
	s_waitcnt lgkmcnt(1)
	v_mfma_f32_32x32x16_bf16 v[16:31], v[74:77], v[78:81], v[16:31]
	s_waitcnt lgkmcnt(0)
	v_mfma_f32_32x32x16_bf16 v[0:15], v[74:77], v[82:85], v[0:15]
	v_bitop3_b32 v74, v223, v132, 14 bitop3:0x36
	v_lshlrev_b32_e32 v135, 4, v74
	v_add_u32_e32 v73, v73, v135
	ds_read_b128 v[74:77], v73
	v_add_u32_e32 v73, v86, v135
	ds_read_b128 v[78:81], v73
	v_add_u32_e32 v73, v87, v135
	ds_read_b128 v[82:85], v73
	s_waitcnt lgkmcnt(0)
	v_mfma_f32_32x32x16_bf16 v[0:15], v[74:77], v[82:85], v[0:15]
	v_cndmask_b32_e64 v73, v66, 0, s[0:1]
	v_lshrrev_b32_e32 v66, 1, v141
	v_lshlrev_b32_e32 v82, 16, v62
	v_and_b32_e32 v83, 0xffff0000, v62
	v_lshlrev_b32_e32 v62, 16, v63
	v_and_b32_e32 v63, 0xffff0000, v63
	s_nop 5
	v_cvt_pk_bf16_f32 v0, v0, v1
	v_mfma_f32_32x32x16_bf16 v[16:31], v[74:77], v[78:81], v[16:31]
	v_cvt_pk_bf16_f32 v1, v2, v3
	v_xor_b32_e32 v2, s71, v132
	v_cndmask_b32_e32 v78, 0, v70, vcc
	v_cndmask_b32_e32 v79, 0, v69, vcc
	v_add_u32_e32 v69, v86, v204
	v_add_u32_e32 v70, v87, v204
	v_lshlrev_b32_e32 v2, 4, v2
	v_add_u32_e32 v3, v69, v2
	v_add_u32_e32 v2, v70, v2
	ds_write_b64 v2, v[0:1] offset:32768
	v_cvt_pk_bf16_f32 v2, v4, v5
	v_xor_b32_e32 v4, s78, v132
	v_lshlrev_b32_e32 v4, 4, v4
	v_cvt_pk_bf16_f32 v0, v20, v21
	v_cvt_pk_bf16_f32 v1, v22, v23
	v_add_u32_e32 v5, v69, v4
	v_cvt_pk_bf16_f32 v16, v16, v17
	v_cvt_pk_bf16_f32 v17, v18, v19
	ds_write_b64 v5, v[0:1] offset:32768
	v_add_u32_e32 v0, v70, v4
	v_xor_b32_e32 v4, s79, v132
	ds_write_b64 v3, v[16:17] offset:32768
	v_cvt_pk_bf16_f32 v3, v6, v7
	v_lshlrev_b32_e32 v4, 4, v4
	ds_write_b64 v0, v[2:3] offset:32768
	v_cvt_pk_bf16_f32 v0, v24, v25
	v_cvt_pk_bf16_f32 v1, v26, v27
	v_add_u32_e32 v5, v69, v4
	ds_write_b64 v5, v[0:1] offset:32768
	v_add_u32_e32 v0, v70, v4
	v_xor_b32_e32 v4, s80, v132
	v_cvt_pk_bf16_f32 v2, v8, v9
	v_cvt_pk_bf16_f32 v3, v10, v11
	v_lshlrev_b32_e32 v4, 4, v4
	ds_write_b64 v0, v[2:3] offset:32768
	v_cvt_pk_bf16_f32 v0, v28, v29
	v_cvt_pk_bf16_f32 v1, v30, v31
	v_cvt_pk_bf16_f32 v2, v12, v13
	v_add_u32_e32 v5, v69, v4
	v_lshlrev_b64 v[12:13], 2, v[130:131]
	v_cvt_pk_bf16_f32 v3, v14, v15
	ds_write_b64 v5, v[0:1] offset:32768
	v_add_u32_e32 v0, v70, v4
	v_lshl_add_u64 v[4:5], s[24:25], 0, v[12:13]
	ds_write_b64 v0, v[2:3] offset:32768
	s_waitcnt lgkmcnt(0)
	s_barrier
; __device__ __forceinline__ unsigned cvtpk(float lo, float hi) { f32x2_t v = {lo, hi}; bf16x2_t b = __builtin_convertvector(v, bf16x2_t); return __builtin_bit_cast(unsigned, b); }
; __device__ __forceinline__ float lo16(unsigned u) { return __uint_as_float(u << 16); }
; __device__ __forceinline__ float hi16(unsigned u) { return __uint_as_float(u & 0xffff0000u); }
; __device__ __forceinline__ float silu_fast(float v) { return v * __builtin_amdgcn_rcpf(1.f + __builtin_amdgcn_exp2f(-v * LOG2E)); }
; __device__ __forceinline__ float lo16(unsigned u) { return __uint_as_float(u << 16); }
; template <class Put>
; __device__ __forceinline__ void conv_compute(const ConvRaw& R, const float* cw, const float* cb, int col0, int rg, const Put& put) {
;     const f32x4 w0a = *(const f32x4*)(cw + col0), w0b = *(const f32x4*)(cw + col0 + 4), w1a = *(const f32x4*)(cw + XBCW + col0), w1b = *(const f32x4*)(cw + XBCW + col0 + 4);
;     const f32x4 w2a = *(const f32x4*)(cw + 2 * XBCW + col0), w2b = *(const f32x4*)(cw + 2 * XBCW + col0 + 4), ba = *(const f32x4*)(cb + col0), bb = *(const f32x4*)(cb + col0 + 4);
;     const int r0 = 8 * rg;
; #pragma unroll
;     for (int rr = 0; rr < 8; ++rr) {
;         const u32x4 xm = R.r[rr], x0 = R.r[rr + 1], xp = R.r[rr + 2]; u32x4 o;
; #pragma unroll
;         for (int e = 0; e < 4; ++e) {
;             const float wl0 = e < 2 ? w0a[2 * e] : w0b[2 * e - 4], wh0 = e < 2 ? w0a[2 * e + 1] : w0b[2 * e - 3];
;             const float wl1 = e < 2 ? w1a[2 * e] : w1b[2 * e - 4], wh1 = e < 2 ? w1a[2 * e + 1] : w1b[2 * e - 3];
;             const float wl2 = e < 2 ? w2a[2 * e] : w2b[2 * e - 4], wh2 = e < 2 ? w2a[2 * e + 1] : w2b[2 * e - 3];
;             const float bl = e < 2 ? ba[2 * e] : bb[2 * e - 4], bh = e < 2 ? ba[2 * e + 1] : bb[2 * e - 3];
;             const float vl = bl + wl0 * lo16(xm[e]) + wl1 * lo16(x0[e]) + wl2 * lo16(xp[e]);
;             const float vh = bh + wh0 * hi16(xm[e]) + wh1 * hi16(x0[e]) + wh2 * hi16(xp[e]);
;             o[e] = cvtpk(silu_fast(vl), silu_fast(vh));
;         }
;         put(r0 + rr, o);
;     }
; }
; template <class Wait>
; __device__ __forceinline__ void out_unit(Frame& F, const Ptrs& P, int b, int c, int g, const Wait& wait) {
;     ...
;     conv_compute(R2, P.conv_w, P.conv_b, col2, rg2, PutTr{lds + L_XS + hl2 * 16384, ch2});
;     wait();
	global_load_dwordx4 v[0:3], v[4:5], off offset:16
	global_load_dwordx4 v[16:19], v[4:5], off
	v_lshl_add_u64 v[4:5], s[30:31], 0, v[12:13]
	v_lshl_add_u64 v[14:15], s[36:37], 0, v[12:13]
	v_lshl_add_u64 v[28:29], s[26:27], 0, v[12:13]
	global_load_dwordx4 v[8:11], v[4:5], off offset:16
	global_load_dwordx4 v[20:23], v[4:5], off
	s_nop 0
	global_load_dwordx4 v[4:7], v[14:15], off offset:16
	global_load_dwordx4 v[24:27], v[14:15], off
	s_nop 0
	global_load_dwordx4 v[12:15], v[28:29], off offset:16
	s_nop 0
	global_load_dwordx4 v[28:31], v[28:29], off
	v_cndmask_b32_e64 v74, v65, 0, s[0:1]
	v_lshlrev_b32_e32 v65, 1, v140
	v_and_or_b32 v65, v65, 8, v66
	v_cndmask_b32_e64 v76, v64, 0, s[0:1]
	v_lshlrev_b32_e32 v64, 14, v142
	v_lshlrev_b32_e32 v65, 10, v65
	v_add3_u32 v64, s69, v64, v65
	v_lshlrev_b32_e32 v65, 9, v141
	v_lshlrev_b32_e32 v66, 4, v140
	v_and_b32_e32 v65, 0x200, v65
	v_and_b32_e32 v66, 48, v66
	v_add3_u32 v75, v64, v65, v66
	v_lshlrev_b32_e32 v64, 16, v68
	v_and_b32_e32 v65, 0xffff0000, v68
	v_lshlrev_b32_e32 v66, 16, v60
	v_cndmask_b32_e32 v77, 0, v71, vcc
	v_lshlrev_b32_e32 v80, 16, v61
	v_and_b32_e32 v81, 0xffff0000, v61
	v_readlane_b32 s0, v252, 11
	v_readlane_b32 s1, v252, 12
	s_andn2_b64 vcc, exec, s[0:1]
	s_waitcnt vmcnt(0)
	v_pk_fma_f32 v[64:65], v[16:17], v[64:65], v[28:29]
	s_nop 0
	v_pk_fma_f32 v[68:69], v[20:21], v[66:67], v[64:65]
	v_lshlrev_b32_e32 v64, 16, v56
	v_and_b32_e32 v65, 0xffff0000, v56
	v_pk_fma_f32 v[68:69], v[24:25], v[64:65], v[68:69]
	v_pk_fma_f32 v[66:67], v[16:17], v[66:67], v[28:29]
	v_mul_f32_e32 v56, 0xbfb8aa3b, v68
	v_exp_f32_e32 v56, v56
	v_pk_fma_f32 v[66:67], v[20:21], v[64:65], v[66:67]
	v_add_f32_e32 v56, 1.0, v56
	v_rcp_f32_e32 v70, v56
	v_mul_f32_e32 v56, 0xbfb8aa3b, v69
	v_exp_f32_e32 v56, v56
	s_nop 0
	v_add_f32_e32 v56, 1.0, v56
	v_rcp_f32_e32 v71, v56
	v_lshlrev_b32_e32 v56, 16, v57
	v_and_b32_e32 v57, 0xffff0000, v57
	v_pk_mul_f32 v[68:69], v[68:69], v[70:71]
	v_lshlrev_b32_e32 v70, 16, v79
	v_and_b32_e32 v71, 0xffff0000, v79
	v_pk_fma_f32 v[70:71], v[18:19], v[70:71], v[30:31]
	v_cvt_pk_bf16_f32 v68, v68, v69
	v_pk_fma_f32 v[60:61], v[22:23], v[80:81], v[70:71]
	s_nop 0
	v_pk_fma_f32 v[60:61], v[26:27], v[56:57], v[60:61]
	s_nop 0
	v_mul_f32_e32 v69, 0xbfb8aa3b, v60
	v_exp_f32_e32 v69, v69
	s_nop 0
	v_add_f32_e32 v69, 1.0, v69
	v_rcp_f32_e32 v70, v69
	v_mul_f32_e32 v69, 0xbfb8aa3b, v61
	v_exp_f32_e32 v69, v69
	s_nop 0
	v_add_f32_e32 v69, 1.0, v69
	v_rcp_f32_e32 v71, v69
	s_nop 0
	v_pk_mul_f32 v[60:61], v[60:61], v[70:71]
	s_nop 0
	v_cvt_pk_bf16_f32 v69, v60, v61
	v_lshlrev_b32_e32 v60, 16, v78
	v_and_b32_e32 v61, 0xffff0000, v78
	v_pk_fma_f32 v[60:61], v[0:1], v[60:61], v[12:13]
	s_nop 0
	v_pk_fma_f32 v[70:71], v[8:9], v[82:83], v[60:61]
	v_lshlrev_b32_e32 v60, 16, v58
	v_and_b32_e32 v61, 0xffff0000, v58
	v_pk_fma_f32 v[70:71], v[4:5], v[60:61], v[70:71]
	s_nop 0
	v_mul_f32_e32 v58, 0xbfb8aa3b, v70
	v_exp_f32_e32 v58, v58
	s_nop 0
	v_add_f32_e32 v58, 1.0, v58
	v_rcp_f32_e32 v78, v58
	v_mul_f32_e32 v58, 0xbfb8aa3b, v71
	v_exp_f32_e32 v58, v58
	s_nop 0
	v_add_f32_e32 v58, 1.0, v58
	v_rcp_f32_e32 v79, v58
	v_lshlrev_b32_e32 v58, 16, v59
	v_and_b32_e32 v59, 0xffff0000, v59
	v_pk_mul_f32 v[70:71], v[70:71], v[78:79]
	v_lshlrev_b32_e32 v78, 16, v77
	v_and_b32_e32 v79, 0xffff0000, v77
	v_pk_fma_f32 v[78:79], v[2:3], v[78:79], v[14:15]
	v_cvt_pk_bf16_f32 v70, v70, v71
	v_pk_fma_f32 v[78:79], v[10:11], v[62:63], v[78:79]
	s_nop 0
	v_pk_fma_f32 v[78:79], v[6:7], v[58:59], v[78:79]
	s_nop 0
	v_mul_f32_e32 v71, 0xbfb8aa3b, v78
	v_exp_f32_e32 v71, v71
	s_nop 0
	v_add_f32_e32 v71, 1.0, v71
	v_rcp_f32_e32 v84, v71
	v_mul_f32_e32 v71, 0xbfb8aa3b, v79
	v_exp_f32_e32 v71, v71
	s_nop 0
	v_add_f32_e32 v71, 1.0, v71
	v_rcp_f32_e32 v85, v71
	s_nop 0
	v_pk_mul_f32 v[78:79], v[78:79], v[84:85]
	s_nop 0
	v_cvt_pk_bf16_f32 v71, v78, v79
	ds_write_b128 v75, v[68:71]
	v_lshlrev_b32_e32 v70, 16, v52
	v_and_b32_e32 v71, 0xffff0000, v52
	v_pk_fma_f32 v[66:67], v[24:25], v[70:71], v[66:67]
	s_nop 0
	v_mul_f32_e32 v52, 0xbfb8aa3b, v66
	v_exp_f32_e32 v52, v52
	s_nop 0
	v_add_f32_e32 v52, 1.0, v52
	v_rcp_f32_e32 v68, v52
	v_mul_f32_e32 v52, 0xbfb8aa3b, v67
	v_exp_f32_e32 v52, v52
	s_nop 0
	v_add_f32_e32 v52, 1.0, v52
	v_rcp_f32_e32 v69, v52
	s_nop 0
	v_pk_mul_f32 v[66:67], v[66:67], v[68:69]
	s_nop 0
	v_cvt_pk_bf16_f32 v78, v66, v67
	v_pk_fma_f32 v[66:67], v[18:19], v[80:81], v[30:31]
	v_lshlrev_b32_e32 v68, 16, v53
	v_pk_fma_f32 v[66:67], v[22:23], v[56:57], v[66:67]
	v_and_b32_e32 v69, 0xffff0000, v53
	v_pk_fma_f32 v[52:53], v[26:27], v[68:69], v[66:67]
	v_pk_fma_f32 v[56:57], v[18:19], v[56:57], v[30:31]
	v_mul_f32_e32 v66, 0xbfb8aa3b, v52
	v_mul_f32_e32 v67, 0xbfb8aa3b, v53
	v_exp_f32_e32 v66, v66
	v_exp_f32_e32 v67, v67
	v_pk_fma_f32 v[56:57], v[22:23], v[68:69], v[56:57]
	v_add_f32_e32 v66, 1.0, v66
	v_add_f32_e32 v67, 1.0, v67
	v_rcp_f32_e32 v66, v66
	v_rcp_f32_e32 v67, v67
	s_nop 0
	v_pk_mul_f32 v[52:53], v[52:53], v[66:67]
	s_nop 0
	v_cvt_pk_bf16_f32 v79, v52, v53
	v_pk_fma_f32 v[52:53], v[0:1], v[82:83], v[12:13]
	v_lshlrev_b32_e32 v66, 16, v54
	v_pk_fma_f32 v[52:53], v[8:9], v[60:61], v[52:53]
	v_and_b32_e32 v67, 0xffff0000, v54
	v_pk_fma_f32 v[52:53], v[4:5], v[66:67], v[52:53]
	s_nop 0
	v_mul_f32_e32 v54, 0xbfb8aa3b, v52
	v_exp_f32_e32 v54, v54
	s_nop 0
	v_add_f32_e32 v54, 1.0, v54
	v_rcp_f32_e32 v80, v54
	v_mul_f32_e32 v54, 0xbfb8aa3b, v53
	v_exp_f32_e32 v54, v54
	s_nop 0
	v_add_f32_e32 v54, 1.0, v54
	v_rcp_f32_e32 v81, v54
	s_nop 0
	v_pk_mul_f32 v[52:53], v[52:53], v[80:81]
	s_nop 0
	v_cvt_pk_bf16_f32 v80, v52, v53
	v_pk_fma_f32 v[52:53], v[2:3], v[62:63], v[14:15]
	s_nop 0
; __device__ __forceinline__ unsigned cvtpk(float lo, float hi) { f32x2_t v = {lo, hi}; bf16x2_t b = __builtin_convertvector(v, bf16x2_t); return __builtin_bit_cast(unsigned, b); }
; __device__ __forceinline__ float lo16(unsigned u) { return __uint_as_float(u << 16); }
; __device__ __forceinline__ float hi16(unsigned u) { return __uint_as_float(u & 0xffff0000u); }
; __device__ __forceinline__ float silu_fast(float v) { return v * __builtin_amdgcn_rcpf(1.f + __builtin_amdgcn_exp2f(-v * LOG2E)); }
; __device__ __forceinline__ unsigned cvtpk(float lo, float hi) { f32x2_t v = {lo, hi}; bf16x2_t b = __builtin_convertvector(v, bf16x2_t); return __builtin_bit_cast(unsigned, b); }
; __device__ __forceinline__ float lo16(unsigned u) { return __uint_as_float(u << 16); }
; __device__ __forceinline__ float hi16(unsigned u) { return __uint_as_float(u & 0xffff0000u); }
; template <class Put>
; __device__ __forceinline__ void conv_compute(const ConvRaw& R, const float* cw, const float* cb, int col0, int rg, const Put& put) {
;     const f32x4 w0a = *(const f32x4*)(cw + col0), w0b = *(const f32x4*)(cw + col0 + 4), w1a = *(const f32x4*)(cw + XBCW + col0), w1b = *(const f32x4*)(cw + XBCW + col0 + 4);
;     const f32x4 w2a = *(const f32x4*)(cw + 2 * XBCW + col0), w2b = *(const f32x4*)(cw + 2 * XBCW + col0 + 4), ba = *(const f32x4*)(cb + col0), bb = *(const f32x4*)(cb + col0 + 4);
;     const int r0 = 8 * rg;
; #pragma unroll
;     for (int rr = 0; rr < 8; ++rr) {
;         const u32x4 xm = R.r[rr], x0 = R.r[rr + 1], xp = R.r[rr + 2]; u32x4 o;
; #pragma unroll
;         for (int e = 0; e < 4; ++e) {
;             const float wl0 = e < 2 ? w0a[2 * e] : w0b[2 * e - 4], wh0 = e < 2 ? w0a[2 * e + 1] : w0b[2 * e - 3];
;             const float wl1 = e < 2 ? w1a[2 * e] : w1b[2 * e - 4], wh1 = e < 2 ? w1a[2 * e + 1] : w1b[2 * e - 3];
;             const float wl2 = e < 2 ? w2a[2 * e] : w2b[2 * e - 4], wh2 = e < 2 ? w2a[2 * e + 1] : w2b[2 * e - 3];
;             const float bl = e < 2 ? ba[2 * e] : bb[2 * e - 4], bh = e < 2 ? ba[2 * e + 1] : bb[2 * e - 3];
;             const float vl = bl + wl0 * lo16(xm[e]) + wl1 * lo16(x0[e]) + wl2 * lo16(xp[e]);
;             const float vh = bh + wh0 * hi16(xm[e]) + wh1 * hi16(x0[e]) + wh2 * hi16(xp[e]);
;             o[e] = cvtpk(silu_fast(vl), silu_fast(vh));
;         }
;         put(r0 + rr, o);
;     }
; }
	v_pk_fma_f32 v[62:63], v[10:11], v[58:59], v[52:53]
	v_lshlrev_b32_e32 v52, 16, v55
	v_and_b32_e32 v53, 0xffff0000, v55
	v_pk_fma_f32 v[54:55], v[6:7], v[52:53], v[62:63]
	v_pk_fma_f32 v[58:59], v[2:3], v[58:59], v[14:15]
	v_mul_f32_e32 v62, 0xbfb8aa3b, v54
	v_mul_f32_e32 v63, 0xbfb8aa3b, v55
	v_exp_f32_e32 v62, v62
	v_exp_f32_e32 v63, v63
	v_pk_fma_f32 v[58:59], v[10:11], v[52:53], v[58:59]
	v_add_f32_e32 v62, 1.0, v62
	v_add_f32_e32 v63, 1.0, v63
	v_rcp_f32_e32 v62, v62
	v_rcp_f32_e32 v63, v63
	s_nop 0
	v_pk_mul_f32 v[54:55], v[54:55], v[62:63]
	s_nop 0
	v_cvt_pk_bf16_f32 v81, v54, v55
	v_pk_fma_f32 v[54:55], v[16:17], v[64:65], v[28:29]
	v_lshlrev_b32_e32 v64, 16, v48
	v_pk_fma_f32 v[54:55], v[20:21], v[70:71], v[54:55]
	v_and_b32_e32 v65, 0xffff0000, v48
	v_pk_fma_f32 v[54:55], v[24:25], v[64:65], v[54:55]
	ds_write_b128 v75, v[78:81] offset:64
	v_mul_f32_e32 v48, 0xbfb8aa3b, v54
	v_exp_f32_e32 v48, v48
	s_nop 0
	v_add_f32_e32 v48, 1.0, v48
	v_rcp_f32_e32 v62, v48
	v_mul_f32_e32 v48, 0xbfb8aa3b, v55
	v_exp_f32_e32 v48, v48
	s_nop 0
	v_add_f32_e32 v48, 1.0, v48
	v_rcp_f32_e32 v63, v48
	v_lshlrev_b32_e32 v48, 16, v49
	v_and_b32_e32 v49, 0xffff0000, v49
	v_pk_fma_f32 v[56:57], v[26:27], v[48:49], v[56:57]
	v_pk_mul_f32 v[54:55], v[54:55], v[62:63]
	s_nop 0
	v_cvt_pk_bf16_f32 v54, v54, v55
	v_mul_f32_e32 v55, 0xbfb8aa3b, v56
	v_exp_f32_e32 v55, v55
	s_nop 0
	v_add_f32_e32 v55, 1.0, v55
	v_rcp_f32_e32 v62, v55
	v_mul_f32_e32 v55, 0xbfb8aa3b, v57
	v_exp_f32_e32 v55, v55
	s_nop 0
	v_add_f32_e32 v55, 1.0, v55
	v_rcp_f32_e32 v63, v55
	s_nop 0
	v_pk_mul_f32 v[56:57], v[56:57], v[62:63]
	s_nop 0
	v_cvt_pk_bf16_f32 v55, v56, v57
	v_pk_fma_f32 v[56:57], v[0:1], v[60:61], v[12:13]
	v_lshlrev_b32_e32 v62, 16, v50
	v_pk_fma_f32 v[56:57], v[8:9], v[66:67], v[56:57]
	v_and_b32_e32 v63, 0xffff0000, v50
	v_pk_fma_f32 v[56:57], v[4:5], v[62:63], v[56:57]
	s_nop 0
	v_mul_f32_e32 v50, 0xbfb8aa3b, v56
	v_exp_f32_e32 v50, v50
	s_nop 0
	v_add_f32_e32 v50, 1.0, v50
	v_rcp_f32_e32 v60, v50
	v_mul_f32_e32 v50, 0xbfb8aa3b, v57
	v_exp_f32_e32 v50, v50
	s_nop 0
	v_add_f32_e32 v50, 1.0, v50
	v_rcp_f32_e32 v61, v50
	s_nop 0
	v_pk_mul_f32 v[56:57], v[56:57], v[60:61]
	v_lshlrev_b32_e32 v60, 16, v51
	v_and_b32_e32 v61, 0xffff0000, v51
	v_pk_fma_f32 v[50:51], v[6:7], v[60:61], v[58:59]
	v_cvt_pk_bf16_f32 v56, v56, v57
	v_mul_f32_e32 v57, 0xbfb8aa3b, v50
	v_exp_f32_e32 v57, v57
	s_nop 0
	v_add_f32_e32 v57, 1.0, v57
	v_rcp_f32_e32 v58, v57
	v_mul_f32_e32 v57, 0xbfb8aa3b, v51
	v_exp_f32_e32 v57, v57
	s_nop 0
	v_add_f32_e32 v57, 1.0, v57
	v_rcp_f32_e32 v59, v57
	s_nop 0
	v_pk_mul_f32 v[50:51], v[50:51], v[58:59]
	s_nop 0
	v_cvt_pk_bf16_f32 v57, v50, v51
	v_pk_fma_f32 v[50:51], v[16:17], v[70:71], v[28:29]
	v_lshlrev_b32_e32 v58, 16, v44
	v_pk_fma_f32 v[50:51], v[20:21], v[64:65], v[50:51]
	v_and_b32_e32 v59, 0xffff0000, v44
	v_pk_fma_f32 v[50:51], v[24:25], v[58:59], v[50:51]
	ds_write_b128 v75, v[54:57] offset:128
	v_mul_f32_e32 v44, 0xbfb8aa3b, v50
	v_exp_f32_e32 v44, v44
	v_lshlrev_b32_e32 v56, 16, v45
	v_and_b32_e32 v57, 0xffff0000, v45
	v_add_f32_e32 v44, 1.0, v44
	v_rcp_f32_e32 v54, v44
	v_mul_f32_e32 v44, 0xbfb8aa3b, v51
	v_exp_f32_e32 v44, v44
	s_nop 0
	v_add_f32_e32 v44, 1.0, v44
	v_rcp_f32_e32 v55, v44
	s_nop 0
	v_pk_mul_f32 v[50:51], v[50:51], v[54:55]
	s_nop 0
	v_cvt_pk_bf16_f32 v44, v50, v51
	v_pk_fma_f32 v[50:51], v[18:19], v[68:69], v[30:31]
	s_nop 0
	v_pk_fma_f32 v[50:51], v[22:23], v[48:49], v[50:51]
	s_nop 0
	v_pk_fma_f32 v[50:51], v[26:27], v[56:57], v[50:51]
	s_nop 0
	v_mul_f32_e32 v45, 0xbfb8aa3b, v50
	v_exp_f32_e32 v45, v45
	s_nop 0
	v_add_f32_e32 v45, 1.0, v45
	v_rcp_f32_e32 v54, v45
	v_mul_f32_e32 v45, 0xbfb8aa3b, v51
	v_exp_f32_e32 v45, v45
	s_nop 0
	v_add_f32_e32 v45, 1.0, v45
	v_rcp_f32_e32 v55, v45
	s_nop 0
	v_pk_mul_f32 v[50:51], v[50:51], v[54:55]
	s_nop 0
	v_cvt_pk_bf16_f32 v45, v50, v51
	v_pk_fma_f32 v[50:51], v[0:1], v[66:67], v[12:13]
	v_lshlrev_b32_e32 v54, 16, v46
	v_pk_fma_f32 v[50:51], v[8:9], v[62:63], v[50:51]
	v_and_b32_e32 v55, 0xffff0000, v46
	v_pk_fma_f32 v[50:51], v[4:5], v[54:55], v[50:51]
	s_nop 0
	v_mul_f32_e32 v46, 0xbfb8aa3b, v50
	v_exp_f32_e32 v46, v46
	s_nop 0
	v_add_f32_e32 v46, 1.0, v46
	v_rcp_f32_e32 v66, v46
	v_mul_f32_e32 v46, 0xbfb8aa3b, v51
	v_exp_f32_e32 v46, v46
	s_nop 0
	v_add_f32_e32 v46, 1.0, v46
	v_rcp_f32_e32 v67, v46
	s_nop 0
	v_pk_mul_f32 v[50:51], v[50:51], v[66:67]
	s_nop 0
	v_cvt_pk_bf16_f32 v46, v50, v51
	v_pk_fma_f32 v[50:51], v[2:3], v[52:53], v[14:15]
	v_lshlrev_b32_e32 v52, 16, v47
	v_pk_fma_f32 v[50:51], v[10:11], v[60:61], v[50:51]
	v_and_b32_e32 v53, 0xffff0000, v47
	v_pk_fma_f32 v[50:51], v[6:7], v[52:53], v[50:51]
	s_nop 0
	v_mul_f32_e32 v47, 0xbfb8aa3b, v50
	v_exp_f32_e32 v47, v47
	s_nop 0
	v_add_f32_e32 v47, 1.0, v47
	v_rcp_f32_e32 v66, v47
	v_mul_f32_e32 v47, 0xbfb8aa3b, v51
	v_exp_f32_e32 v47, v47
	s_nop 0
	v_add_f32_e32 v47, 1.0, v47
	v_rcp_f32_e32 v67, v47
	s_nop 0
	v_pk_mul_f32 v[50:51], v[50:51], v[66:67]
	s_nop 0
	v_cvt_pk_bf16_f32 v47, v50, v51
	ds_write_b128 v75, v[44:47] offset:192
	v_pk_fma_f32 v[44:45], v[16:17], v[64:65], v[28:29]
	v_lshlrev_b32_e32 v50, 16, v40
	v_pk_fma_f32 v[44:45], v[20:21], v[58:59], v[44:45]
	v_and_b32_e32 v51, 0xffff0000, v40
	v_pk_fma_f32 v[44:45], v[24:25], v[50:51], v[44:45]
	s_nop 0
	v_mul_f32_e32 v40, 0xbfb8aa3b, v44
	v_exp_f32_e32 v40, v40
	s_nop 0
	v_add_f32_e32 v40, 1.0, v40
	v_rcp_f32_e32 v46, v40
	v_mul_f32_e32 v40, 0xbfb8aa3b, v45
	v_exp_f32_e32 v40, v40
	s_nop 0
	v_add_f32_e32 v40, 1.0, v40
	v_rcp_f32_e32 v47, v40
	s_nop 0
	v_pk_mul_f32 v[44:45], v[44:45], v[46:47]
	s_nop 0
	v_cvt_pk_bf16_f32 v40, v44, v45
	v_pk_fma_f32 v[44:45], v[18:19], v[48:49], v[30:31]
; __device__ __forceinline__ unsigned cvtpk(float lo, float hi) { f32x2_t v = {lo, hi}; bf16x2_t b = __builtin_convertvector(v, bf16x2_t); return __builtin_bit_cast(unsigned, b); }
; __device__ __forceinline__ float lo16(unsigned u) { return __uint_as_float(u << 16); }
; __device__ __forceinline__ float hi16(unsigned u) { return __uint_as_float(u & 0xffff0000u); }
; __device__ __forceinline__ float silu_fast(float v) { return v * __builtin_amdgcn_rcpf(1.f + __builtin_amdgcn_exp2f(-v * LOG2E)); }
; __device__ __forceinline__ unsigned cvtpk(float lo, float hi) { f32x2_t v = {lo, hi}; bf16x2_t b = __builtin_convertvector(v, bf16x2_t); return __builtin_bit_cast(unsigned, b); }
; __device__ __forceinline__ float lo16(unsigned u) { return __uint_as_float(u << 16); }
; __device__ __forceinline__ float hi16(unsigned u) { return __uint_as_float(u & 0xffff0000u); }
; __device__ __forceinline__ float silu_fast(float v) { return v * __builtin_amdgcn_rcpf(1.f + __builtin_amdgcn_exp2f(-v * LOG2E)); }
; template <class Put>
; __device__ __forceinline__ void conv_compute(const ConvRaw& R, const float* cw, const float* cb, int col0, int rg, const Put& put) {
;     ...
;     for (int rr = 0; rr < 8; ++rr) {
;         const u32x4 xm = R.r[rr], x0 = R.r[rr + 1], xp = R.r[rr + 2]; u32x4 o;
; #pragma unroll
;         for (int e = 0; e < 4; ++e) {
;             const float wl0 = e < 2 ? w0a[2 * e] : w0b[2 * e - 4], wh0 = e < 2 ? w0a[2 * e + 1] : w0b[2 * e - 3];
;             const float wl1 = e < 2 ? w1a[2 * e] : w1b[2 * e - 4], wh1 = e < 2 ? w1a[2 * e + 1] : w1b[2 * e - 3];
;             const float wl2 = e < 2 ? w2a[2 * e] : w2b[2 * e - 4], wh2 = e < 2 ? w2a[2 * e + 1] : w2b[2 * e - 3];
;             const float bl = e < 2 ? ba[2 * e] : bb[2 * e - 4], bh = e < 2 ? ba[2 * e + 1] : bb[2 * e - 3];
;             const float vl = bl + wl0 * lo16(xm[e]) + wl1 * lo16(x0[e]) + wl2 * lo16(xp[e]);
;             const float vh = bh + wh0 * hi16(xm[e]) + wh1 * hi16(x0[e]) + wh2 * hi16(xp[e]);
;             o[e] = cvtpk(silu_fast(vl), silu_fast(vh));
;         }
;         put(r0 + rr, o);
;     }
	v_lshlrev_b32_e32 v48, 16, v41
	v_pk_fma_f32 v[44:45], v[22:23], v[56:57], v[44:45]
	v_and_b32_e32 v49, 0xffff0000, v41
	v_pk_fma_f32 v[44:45], v[26:27], v[48:49], v[44:45]
	s_nop 0
	v_mul_f32_e32 v41, 0xbfb8aa3b, v44
	v_exp_f32_e32 v41, v41
	s_nop 0
	v_add_f32_e32 v41, 1.0, v41
	v_rcp_f32_e32 v46, v41
	v_mul_f32_e32 v41, 0xbfb8aa3b, v45
	v_exp_f32_e32 v41, v41
	s_nop 0
	v_add_f32_e32 v41, 1.0, v41
	v_rcp_f32_e32 v47, v41
	s_nop 0
	v_pk_mul_f32 v[44:45], v[44:45], v[46:47]
	s_nop 0
	v_cvt_pk_bf16_f32 v41, v44, v45
	v_pk_fma_f32 v[44:45], v[0:1], v[62:63], v[12:13]
	v_lshlrev_b32_e32 v46, 16, v42
	v_pk_fma_f32 v[44:45], v[8:9], v[54:55], v[44:45]
	v_and_b32_e32 v47, 0xffff0000, v42
	v_pk_fma_f32 v[44:45], v[4:5], v[46:47], v[44:45]
	s_nop 0
	v_mul_f32_e32 v42, 0xbfb8aa3b, v44
	v_exp_f32_e32 v42, v42
	s_nop 0
	v_add_f32_e32 v42, 1.0, v42
	v_rcp_f32_e32 v62, v42
	v_mul_f32_e32 v42, 0xbfb8aa3b, v45
	v_exp_f32_e32 v42, v42
	s_nop 0
	v_add_f32_e32 v42, 1.0, v42
	v_rcp_f32_e32 v63, v42
	s_nop 0
	v_pk_mul_f32 v[44:45], v[44:45], v[62:63]
	s_nop 0
	v_cvt_pk_bf16_f32 v42, v44, v45
	v_pk_fma_f32 v[44:45], v[2:3], v[60:61], v[14:15]
	s_nop 0
	v_pk_fma_f32 v[60:61], v[10:11], v[52:53], v[44:45]
	v_lshlrev_b32_e32 v44, 16, v43
	v_and_b32_e32 v45, 0xffff0000, v43
	v_pk_fma_f32 v[60:61], v[6:7], v[44:45], v[60:61]
	v_pk_fma_f32 v[52:53], v[2:3], v[52:53], v[14:15]
	v_mul_f32_e32 v43, 0xbfb8aa3b, v60
	v_exp_f32_e32 v43, v43
	v_pk_fma_f32 v[52:53], v[10:11], v[44:45], v[52:53]
	v_pk_fma_f32 v[44:45], v[2:3], v[44:45], v[14:15]
	v_add_f32_e32 v43, 1.0, v43
	v_rcp_f32_e32 v62, v43
	v_mul_f32_e32 v43, 0xbfb8aa3b, v61
	v_exp_f32_e32 v43, v43
	s_nop 0
	v_add_f32_e32 v43, 1.0, v43
	v_rcp_f32_e32 v63, v43
	s_nop 0
	v_pk_mul_f32 v[60:61], v[60:61], v[62:63]
	s_nop 0
	v_cvt_pk_bf16_f32 v43, v60, v61
	ds_write_b128 v75, v[40:43] offset:256
	v_pk_fma_f32 v[40:41], v[16:17], v[58:59], v[28:29]
	v_lshlrev_b32_e32 v42, 16, v36
	v_pk_fma_f32 v[40:41], v[20:21], v[50:51], v[40:41]
	v_and_b32_e32 v43, 0xffff0000, v36
	v_pk_fma_f32 v[40:41], v[24:25], v[42:43], v[40:41]
	v_pk_fma_f32 v[50:51], v[16:17], v[50:51], v[28:29]
	v_mul_f32_e32 v36, 0xbfb8aa3b, v40
	v_exp_f32_e32 v36, v36
	v_pk_fma_f32 v[50:51], v[20:21], v[42:43], v[50:51]
	v_pk_fma_f32 v[16:17], v[16:17], v[42:43], v[28:29]
	v_add_f32_e32 v36, 1.0, v36
	v_rcp_f32_e32 v58, v36
	v_mul_f32_e32 v36, 0xbfb8aa3b, v41
	v_exp_f32_e32 v36, v36
	s_nop 0
	v_add_f32_e32 v36, 1.0, v36
	v_rcp_f32_e32 v59, v36
	s_nop 0
	v_pk_mul_f32 v[40:41], v[40:41], v[58:59]
	s_nop 0
	v_cvt_pk_bf16_f32 v58, v40, v41
	v_pk_fma_f32 v[40:41], v[18:19], v[56:57], v[30:31]
	s_nop 0
	v_pk_fma_f32 v[56:57], v[22:23], v[48:49], v[40:41]
	v_lshlrev_b32_e32 v40, 16, v37
	v_and_b32_e32 v41, 0xffff0000, v37
	v_pk_fma_f32 v[36:37], v[26:27], v[40:41], v[56:57]
	v_pk_fma_f32 v[48:49], v[18:19], v[48:49], v[30:31]
	v_mul_f32_e32 v56, 0xbfb8aa3b, v36
	v_mul_f32_e32 v57, 0xbfb8aa3b, v37
	v_exp_f32_e32 v56, v56
	v_exp_f32_e32 v57, v57
	v_pk_fma_f32 v[48:49], v[22:23], v[40:41], v[48:49]
	v_pk_fma_f32 v[18:19], v[18:19], v[40:41], v[30:31]
	v_add_f32_e32 v56, 1.0, v56
	v_add_f32_e32 v57, 1.0, v57
	v_rcp_f32_e32 v56, v56
	v_rcp_f32_e32 v57, v57
	s_nop 0
	v_pk_mul_f32 v[36:37], v[36:37], v[56:57]
	s_nop 0
	v_cvt_pk_bf16_f32 v59, v36, v37
	v_pk_fma_f32 v[36:37], v[0:1], v[54:55], v[12:13]
	s_nop 0
	v_pk_fma_f32 v[54:55], v[8:9], v[46:47], v[36:37]
	v_lshlrev_b32_e32 v36, 16, v38
	v_and_b32_e32 v37, 0xffff0000, v38
	v_pk_fma_f32 v[54:55], v[4:5], v[36:37], v[54:55]
	v_pk_fma_f32 v[46:47], v[0:1], v[46:47], v[12:13]
	v_mul_f32_e32 v38, 0xbfb8aa3b, v54
	v_exp_f32_e32 v38, v38
	v_pk_fma_f32 v[46:47], v[8:9], v[36:37], v[46:47]
	v_pk_fma_f32 v[0:1], v[0:1], v[36:37], v[12:13]
	v_add_f32_e32 v38, 1.0, v38
	v_rcp_f32_e32 v56, v38
	v_mul_f32_e32 v38, 0xbfb8aa3b, v55
	v_exp_f32_e32 v38, v38
	s_nop 0
	v_add_f32_e32 v38, 1.0, v38
	v_rcp_f32_e32 v57, v38
	v_lshlrev_b32_e32 v38, 16, v39
	v_and_b32_e32 v39, 0xffff0000, v39
	v_pk_fma_f32 v[52:53], v[6:7], v[38:39], v[52:53]
	v_pk_mul_f32 v[54:55], v[54:55], v[56:57]
	v_pk_fma_f32 v[44:45], v[10:11], v[38:39], v[44:45]
	v_cvt_pk_bf16_f32 v60, v54, v55
	v_mul_f32_e32 v54, 0xbfb8aa3b, v52
	v_mul_f32_e32 v55, 0xbfb8aa3b, v53
	v_exp_f32_e32 v54, v54
	v_exp_f32_e32 v55, v55
	v_add_f32_e32 v54, 1.0, v54
	v_add_f32_e32 v55, 1.0, v55
	v_rcp_f32_e32 v54, v54
	v_rcp_f32_e32 v55, v55
	s_nop 0
	v_pk_mul_f32 v[52:53], v[52:53], v[54:55]
	s_nop 0
; __device__ __forceinline__ unsigned xb_ld(unsigned* p)              { return __hip_atomic_load(p, __ATOMIC_RELAXED, __HIP_MEMORY_SCOPE_AGENT); }
; #define XB_SPIN(cond, bar) do { unsigned _sp = 0; while (cond) { __builtin_amdgcn_s_sleep(1); \
;     if ((++_sp & 255u) == 0u) { if (xb_ld(&(bar)[XB_TMO])) break; if (_sp > XB_SPIN_CAP) { atomicAdd(&(bar)[XB_TMO], 1u); break; } } } } while (0)
; __device__ __forceinline__ bool xb_thread0(int wave) { return wave == 0 && hw_lane() == 0; }
; __device__ __forceinline__ unsigned cvtpk(float lo, float hi) { f32x2_t v = {lo, hi}; bf16x2_t b = __builtin_convertvector(v, bf16x2_t); return __builtin_bit_cast(unsigned, b); }
; __device__ __forceinline__ float lo16(unsigned u) { return __uint_as_float(u << 16); }
; __device__ __forceinline__ float hi16(unsigned u) { return __uint_as_float(u & 0xffff0000u); }
; __device__ __forceinline__ float lo16(unsigned u) { return __uint_as_float(u << 16); }
; __device__ __forceinline__ void xcd_barrier_wait(const XcdBarrier& b) {
;     if (xb_thread0(b.wave)) {
;         const unsigned g = b.st[2];
;         XB_SPIN(xb_ld(&b.bar[XB_TOPGEN]) <= g, b.bar);
;         __builtin_amdgcn_fence(__ATOMIC_ACQUIRE, "agent");
;         asm volatile("s_waitcnt vmcnt(0)" ::: "memory");
;     }
;     __syncthreads();
; }
; template <class Put>
; __device__ __forceinline__ void conv_compute(const ConvRaw& R, const float* cw, const float* cb, int col0, int rg, const Put& put) {
;     ...
;     for (int rr = 0; rr < 8; ++rr) {
;         const u32x4 xm = R.r[rr], x0 = R.r[rr + 1], xp = R.r[rr + 2]; u32x4 o;
; #pragma unroll
;         for (int e = 0; e < 4; ++e) {
;             const float wl0 = e < 2 ? w0a[2 * e] : w0b[2 * e - 4], wh0 = e < 2 ? w0a[2 * e + 1] : w0b[2 * e - 3];
;             const float wl1 = e < 2 ? w1a[2 * e] : w1b[2 * e - 4], wh1 = e < 2 ? w1a[2 * e + 1] : w1b[2 * e - 3];
;             const float wl2 = e < 2 ? w2a[2 * e] : w2b[2 * e - 4], wh2 = e < 2 ? w2a[2 * e + 1] : w2b[2 * e - 3];
;             const float bl = e < 2 ? ba[2 * e] : bb[2 * e - 4], bh = e < 2 ? ba[2 * e + 1] : bb[2 * e - 3];
;             const float vl = bl + wl0 * lo16(xm[e]) + wl1 * lo16(x0[e]) + wl2 * lo16(xp[e]);
;             const float vh = bh + wh0 * hi16(xm[e]) + wh1 * hi16(x0[e]) + wh2 * hi16(xp[e]);
;             o[e] = cvtpk(silu_fast(vl), silu_fast(vh));
;         }
;         put(r0 + rr, o);
;     }
	v_cvt_pk_bf16_f32 v61, v52, v53
	v_lshlrev_b32_e32 v52, 16, v32
	v_and_b32_e32 v53, 0xffff0000, v32
	v_pk_fma_f32 v[50:51], v[24:25], v[52:53], v[50:51]
	v_pk_fma_f32 v[16:17], v[20:21], v[52:53], v[16:17]
	v_mul_f32_e32 v32, 0xbfb8aa3b, v50
	v_exp_f32_e32 v32, v32
	ds_write_b128 v75, v[58:61] offset:320
	v_add_f32_e32 v32, 1.0, v32
	v_rcp_f32_e32 v54, v32
	v_mul_f32_e32 v32, 0xbfb8aa3b, v51
	v_exp_f32_e32 v32, v32
	s_nop 0
	v_add_f32_e32 v32, 1.0, v32
	v_rcp_f32_e32 v55, v32
	s_nop 0
	v_pk_mul_f32 v[50:51], v[50:51], v[54:55]
	s_nop 0
	v_cvt_pk_bf16_f32 v32, v50, v51
	v_lshlrev_b32_e32 v50, 16, v33
	v_and_b32_e32 v51, 0xffff0000, v33
	v_pk_fma_f32 v[48:49], v[26:27], v[50:51], v[48:49]
	v_pk_fma_f32 v[18:19], v[22:23], v[50:51], v[18:19]
	v_mul_f32_e32 v33, 0xbfb8aa3b, v48
	v_exp_f32_e32 v33, v33
	s_nop 0
	v_add_f32_e32 v33, 1.0, v33
	v_rcp_f32_e32 v54, v33
	v_mul_f32_e32 v33, 0xbfb8aa3b, v49
	v_exp_f32_e32 v33, v33
	s_nop 0
	v_add_f32_e32 v33, 1.0, v33
	v_rcp_f32_e32 v55, v33
	s_nop 0
	v_pk_mul_f32 v[48:49], v[48:49], v[54:55]
	s_nop 0
	v_cvt_pk_bf16_f32 v33, v48, v49
	v_lshlrev_b32_e32 v48, 16, v34
	v_and_b32_e32 v49, 0xffff0000, v34
	v_pk_fma_f32 v[46:47], v[4:5], v[48:49], v[46:47]
	v_pk_fma_f32 v[0:1], v[8:9], v[48:49], v[0:1]
	v_mul_f32_e32 v34, 0xbfb8aa3b, v46
	v_exp_f32_e32 v34, v34
	s_nop 0
	v_add_f32_e32 v34, 1.0, v34
	v_rcp_f32_e32 v54, v34
	v_mul_f32_e32 v34, 0xbfb8aa3b, v47
	v_exp_f32_e32 v34, v34
	s_nop 0
	v_add_f32_e32 v34, 1.0, v34
	v_rcp_f32_e32 v55, v34
	s_nop 0
	v_pk_mul_f32 v[46:47], v[46:47], v[54:55]
	s_nop 0
	v_cvt_pk_bf16_f32 v34, v46, v47
	v_lshlrev_b32_e32 v46, 16, v35
	v_and_b32_e32 v47, 0xffff0000, v35
	v_pk_fma_f32 v[44:45], v[6:7], v[46:47], v[44:45]
	s_nop 0
	v_mul_f32_e32 v35, 0xbfb8aa3b, v44
	v_exp_f32_e32 v35, v35
	s_nop 0
	v_add_f32_e32 v35, 1.0, v35
	v_rcp_f32_e32 v54, v35
	v_mul_f32_e32 v35, 0xbfb8aa3b, v45
	v_exp_f32_e32 v35, v35
	s_nop 0
	v_add_f32_e32 v35, 1.0, v35
	v_rcp_f32_e32 v55, v35
	s_nop 0
	v_pk_mul_f32 v[44:45], v[44:45], v[54:55]
	s_nop 0
	v_cvt_pk_bf16_f32 v35, v44, v45
	ds_write_b128 v75, v[32:35] offset:384
	v_lshlrev_b32_e32 v32, 16, v76
	v_and_b32_e32 v33, 0xffff0000, v76
	v_pk_fma_f32 v[16:17], v[24:25], v[32:33], v[16:17]
	s_nop 0
	v_mul_f32_e32 v20, 0xbfb8aa3b, v16
	v_mul_f32_e32 v21, 0xbfb8aa3b, v17
	v_exp_f32_e32 v20, v20
	v_exp_f32_e32 v21, v21
	v_add_f32_e32 v20, 1.0, v20
	v_add_f32_e32 v21, 1.0, v21
	v_rcp_f32_e32 v20, v20
	v_rcp_f32_e32 v21, v21
	s_nop 0
	v_pk_mul_f32 v[16:17], v[16:17], v[20:21]
	v_lshlrev_b32_e32 v20, 16, v74
	v_and_b32_e32 v21, 0xffff0000, v74
	v_pk_fma_f32 v[18:19], v[26:27], v[20:21], v[18:19]
	v_cvt_pk_bf16_f32 v16, v16, v17
	v_mul_f32_e32 v17, 0xbfb8aa3b, v18
	v_exp_f32_e32 v17, v17
	s_nop 0
	v_add_f32_e32 v17, 1.0, v17
	v_rcp_f32_e32 v20, v17
	v_mul_f32_e32 v17, 0xbfb8aa3b, v19
	v_exp_f32_e32 v17, v17
	s_nop 0
	v_add_f32_e32 v17, 1.0, v17
	v_rcp_f32_e32 v21, v17
	s_nop 0
	v_pk_mul_f32 v[18:19], v[18:19], v[20:21]
	s_nop 0
	v_cvt_pk_bf16_f32 v17, v18, v19
	v_lshlrev_b32_e32 v18, 16, v73
	v_and_b32_e32 v19, 0xffff0000, v73
	v_pk_fma_f32 v[0:1], v[4:5], v[18:19], v[0:1]
	s_nop 0
	v_mul_f32_e32 v4, 0xbfb8aa3b, v0
	v_mul_f32_e32 v5, 0xbfb8aa3b, v1
	v_exp_f32_e32 v4, v4
	v_exp_f32_e32 v5, v5
	v_add_f32_e32 v4, 1.0, v4
	v_add_f32_e32 v5, 1.0, v5
	v_rcp_f32_e32 v4, v4
	v_rcp_f32_e32 v5, v5
	s_nop 0
	v_pk_mul_f32 v[0:1], v[0:1], v[4:5]
	s_nop 0
	v_cvt_pk_bf16_f32 v18, v0, v1
	v_pk_fma_f32 v[0:1], v[2:3], v[38:39], v[14:15]
	v_lshlrev_b32_e32 v2, 16, v72
	v_pk_fma_f32 v[0:1], v[10:11], v[46:47], v[0:1]
	v_and_b32_e32 v3, 0xffff0000, v72
	v_pk_fma_f32 v[0:1], v[6:7], v[2:3], v[0:1]
	s_nop 0
	v_mul_f32_e32 v2, 0xbfb8aa3b, v0
	v_mul_f32_e32 v3, 0xbfb8aa3b, v1
	v_exp_f32_e32 v2, v2
	v_exp_f32_e32 v3, v3
	v_add_f32_e32 v2, 1.0, v2
	v_add_f32_e32 v3, 1.0, v3
	v_rcp_f32_e32 v2, v2
	v_rcp_f32_e32 v3, v3
	s_nop 0
	v_pk_mul_f32 v[0:1], v[0:1], v[2:3]
	s_nop 0
	v_cvt_pk_bf16_f32 v19, v0, v1
	ds_write_b128 v75, v[16:19] offset:448
	s_cbranch_vccnz .LBB0_741
	v_mbcnt_lo_u32_b32 v0, -1, 0
	v_mbcnt_hi_u32_b32 v0, -1, v0
	s_nop 0
	v_cmp_eq_u32_e32 vcc, 0, v0
	s_and_saveexec_b64 s[0:1], vcc
	s_cbranch_execz .LBB0_740
	v_mov_b32_e32 v0, s33
	ds_read2_b32 v[0:1], v0 offset1:1
	s_waitcnt lgkmcnt(0)
	v_mad_u32_u24 v0, v1, v0, v0
	v_add_u32_e32 v0, -1, v0
	global_load_dword v1, v201, s[38:39] sc1
	s_waitcnt vmcnt(0)
	v_cmp_gt_u32_e32 vcc, v1, v0
	s_cbranch_vccnz .LBB0_739
	s_mov_b32 s8, 1
	s_branch .LBB0_729
